# GEMM K-loops: first iteration peeled with SrcC=0, accumulator zero-fill (128 v_mov per unit) removed
# speedup vs baseline: 1.0341x; 1.0021x over previous
.LBB0_314:
	v_mov_b64_e32 v[2:3], s[66:67]
	s_ashr_i32 s9, s8, 31
	v_cmp_lt_i64_e32 vcc, s[6:7], v[2:3]
	s_lshl_b64 s[6:7], s[8:9], 19
	s_add_u32 s36, s74, s6
	s_addc_u32 s37, s75, s7
	s_and_b64 s[6:7], vcc, exec
	s_cselect_b32 s18, s37, s13
	s_cselect_b32 s19, s36, s12
	s_ashr_i32 s91, s90, 31
	s_lshl_b64 s[6:7], s[90:91], 19
	s_add_u32 s6, s62, s6
	s_addc_u32 s7, s63, s7
	s_and_b64 s[16:17], vcc, exec
	s_cselect_b32 s20, s7, s15
	s_cselect_b32 s21, s6, s14
	s_add_u32 s12, s12, 0x40080
	s_addc_u32 s13, s13, 0
	s_add_u32 s22, s14, 0x100
	s_addc_u32 s23, s15, 0
	s_mov_b32 s28, -2
	s_add_u32 s14, s12, 0xfffc0080
	s_addc_u32 s15, s13, -1
	s_add_i32 s29, 0, 0x10000
	v_add_u32_e32 v0, s29, v188
	ds_read_b128 v[130:133], v0
	ds_read_b128 v[134:137], v0 offset:1024
	ds_read_b128 v[138:141], v0 offset:2048
	ds_read_b128 v[142:145], v0 offset:3072
	s_cmp_eq_u32 s28, 12
	s_cselect_b32 s17, s18, s15
	s_cselect_b32 s16, s19, s14
	s_cselect_b32 s15, s20, s23
	s_cselect_b32 s14, s21, s22
	v_lshl_add_u64 v[208:209], s[12:13], 0, v[172:173]
	s_add_i32 m0, s65, 0xc000
	ds_read_b128 v[146:149], v203
	ds_read_b128 v[150:153], v203 offset:1024
	ds_read_b128 v[154:157], v203 offset:2048
	ds_read_b128 v[158:161], v203 offset:3072
	ds_read_b128 v[184:187], v203 offset:4096
	ds_read_b128 v[204:207], v203 offset:5120
	ds_read_b128 v[236:239], v203 offset:6144
	ds_read_b128 v[240:243], v203 offset:7168
	global_load_lds_dwordx4 v[208:209], off
	v_lshl_add_u64 v[208:209], s[12:13], 0, v[174:175]
	s_add_i32 m0, s65, 0xe000
	s_nop 0
	global_load_lds_dwordx4 v[208:209], off
	s_waitcnt lgkmcnt(8)
	s_barrier
	s_waitcnt lgkmcnt(0)
	s_setprio 1
	s_waitcnt lgkmcnt(0)
	v_mfma_f32_16x16x32_bf16 v[122:125], v[130:133], v[146:149], 0
	v_mfma_f32_16x16x32_bf16 v[126:129], v[138:141], v[146:149], 0
	v_mfma_f32_16x16x32_bf16 v[114:117], v[130:133], v[154:157], 0
	v_mfma_f32_16x16x32_bf16 v[118:121], v[138:141], v[154:157], 0
	v_mfma_f32_16x16x32_bf16 v[106:109], v[130:133], v[184:187], 0
	v_mfma_f32_16x16x32_bf16 v[110:113], v[138:141], v[184:187], 0
	v_mfma_f32_16x16x32_bf16 v[98:101], v[130:133], v[236:239], 0
	v_mfma_f32_16x16x32_bf16 v[102:105], v[138:141], v[236:239], 0
	v_mfma_f32_16x16x32_bf16 v[122:125], v[134:137], v[150:153], v[122:125]
	v_mfma_f32_16x16x32_bf16 v[126:129], v[142:145], v[150:153], v[126:129]
	v_mfma_f32_16x16x32_bf16 v[114:117], v[134:137], v[158:161], v[114:117]
	v_mfma_f32_16x16x32_bf16 v[118:121], v[142:145], v[158:161], v[118:121]
	v_mfma_f32_16x16x32_bf16 v[106:109], v[134:137], v[204:207], v[106:109]
	v_mfma_f32_16x16x32_bf16 v[110:113], v[142:145], v[204:207], v[110:113]
	v_mfma_f32_16x16x32_bf16 v[98:101], v[134:137], v[240:243], v[98:101]
	v_mfma_f32_16x16x32_bf16 v[102:105], v[142:145], v[240:243], v[102:105]
	s_setprio 0
	s_barrier
	s_add_i32 s72, 0, 0x14000
	s_add_i32 s29, s29, s64
	v_add_u32_e32 v0, s72, v188
	v_lshl_add_u64 v[208:209], s[14:15], 0, v[164:165]
	s_mov_b32 m0, s29
	ds_read_b128 v[244:247], v0
	ds_read_b128 v[248:251], v0 offset:1024
	ds_read_b128 v[212:215], v0 offset:2048
	ds_read_b128 v[216:219], v0 offset:3072
	global_load_lds_dwordx4 v[208:209], off
	v_lshl_add_u64 v[230:231], s[14:15], 0, v[168:169]
	s_add_i32 m0, s29, 0x2000
	s_nop 0
	global_load_lds_dwordx4 v[230:231], off
	s_barrier
	s_waitcnt lgkmcnt(0)
	s_setprio 1
	s_waitcnt lgkmcnt(0)
	v_mfma_f32_16x16x32_bf16 v[90:93], v[244:247], v[146:149], 0
	v_mfma_f32_16x16x32_bf16 v[94:97], v[212:215], v[146:149], 0
	v_mfma_f32_16x16x32_bf16 v[82:85], v[244:247], v[154:157], 0
	v_mfma_f32_16x16x32_bf16 v[86:89], v[212:215], v[154:157], 0
	v_mfma_f32_16x16x32_bf16 v[74:77], v[244:247], v[184:187], 0
	v_mfma_f32_16x16x32_bf16 v[78:81], v[212:215], v[184:187], 0
	v_mfma_f32_16x16x32_bf16 v[66:69], v[244:247], v[236:239], 0
	v_mfma_f32_16x16x32_bf16 v[70:73], v[212:215], v[236:239], 0
	v_mfma_f32_16x16x32_bf16 v[90:93], v[248:251], v[150:153], v[90:93]
	v_mfma_f32_16x16x32_bf16 v[94:97], v[216:219], v[150:153], v[94:97]
	v_mfma_f32_16x16x32_bf16 v[82:85], v[248:251], v[158:161], v[82:85]
	v_mfma_f32_16x16x32_bf16 v[86:89], v[216:219], v[158:161], v[86:89]
	v_mfma_f32_16x16x32_bf16 v[74:77], v[248:251], v[204:207], v[74:77]
	v_mfma_f32_16x16x32_bf16 v[78:81], v[216:219], v[204:207], v[78:81]
	v_mfma_f32_16x16x32_bf16 v[66:69], v[248:251], v[240:243], v[66:69]
	v_mfma_f32_16x16x32_bf16 v[70:73], v[216:219], v[240:243], v[70:73]
	s_setprio 0
	s_mov_b32 m0, s65
	v_lshl_add_u64 v[222:223], s[16:17], 0, v[162:163]
	s_barrier
	ds_read_b128 v[146:149], v203 offset:16384
	ds_read_b128 v[150:153], v203 offset:17408
	ds_read_b128 v[154:157], v203 offset:18432
	ds_read_b128 v[158:161], v203 offset:19456
	ds_read_b128 v[184:187], v203 offset:20480
	ds_read_b128 v[204:207], v203 offset:21504
	ds_read_b128 v[236:239], v203 offset:22528
	ds_read_b128 v[240:243], v203 offset:23552
	global_load_lds_dwordx4 v[222:223], off
	v_lshl_add_u64 v[232:233], s[16:17], 0, v[166:167]
	s_mov_b32 m0, s89
	s_nop 0
	global_load_lds_dwordx4 v[232:233], off
	s_barrier
	s_waitcnt lgkmcnt(0)
	s_setprio 1
	s_waitcnt lgkmcnt(0)
	v_mfma_f32_16x16x32_bf16 v[58:61], v[130:133], v[146:149], 0
	v_mfma_f32_16x16x32_bf16 v[62:65], v[138:141], v[146:149], 0
	v_mfma_f32_16x16x32_bf16 v[50:53], v[130:133], v[154:157], 0
	v_mfma_f32_16x16x32_bf16 v[54:57], v[138:141], v[154:157], 0
	v_mfma_f32_16x16x32_bf16 v[42:45], v[130:133], v[184:187], 0
	v_mfma_f32_16x16x32_bf16 v[46:49], v[138:141], v[184:187], 0
	v_mfma_f32_16x16x32_bf16 v[34:37], v[130:133], v[236:239], 0
	v_mfma_f32_16x16x32_bf16 v[38:41], v[138:141], v[236:239], 0
	v_mfma_f32_16x16x32_bf16 v[58:61], v[134:137], v[150:153], v[58:61]
	v_mfma_f32_16x16x32_bf16 v[62:65], v[142:145], v[150:153], v[62:65]
	v_mfma_f32_16x16x32_bf16 v[50:53], v[134:137], v[158:161], v[50:53]
	v_mfma_f32_16x16x32_bf16 v[54:57], v[142:145], v[158:161], v[54:57]
	v_mfma_f32_16x16x32_bf16 v[42:45], v[134:137], v[204:207], v[42:45]
	v_mfma_f32_16x16x32_bf16 v[46:49], v[142:145], v[204:207], v[46:49]
	v_mfma_f32_16x16x32_bf16 v[34:37], v[134:137], v[240:243], v[34:37]
	v_mfma_f32_16x16x32_bf16 v[38:41], v[142:145], v[240:243], v[38:41]
	s_setprio 0
	s_barrier
	s_add_u32 s34, s14, 0x40000
	s_addc_u32 s35, s15, 0
	s_add_i32 s29, s72, s64
	v_lshl_add_u64 v[130:131], s[34:35], 0, v[164:165]
	s_mov_b32 m0, s29
	s_nop 0
	global_load_lds_dwordx4 v[130:131], off
	v_lshl_add_u64 v[130:131], s[34:35], 0, v[168:169]
	s_add_i32 m0, s29, 0x2000
	s_nop 0
	global_load_lds_dwordx4 v[130:131], off
	s_waitcnt vmcnt(6)
	s_barrier
	s_setprio 1
	v_mfma_f32_16x16x32_bf16 v[26:29], v[244:247], v[146:149], 0
	v_mfma_f32_16x16x32_bf16 v[30:33], v[212:215], v[146:149], 0
	v_mfma_f32_16x16x32_bf16 v[18:21], v[244:247], v[154:157], 0
	v_mfma_f32_16x16x32_bf16 v[22:25], v[212:215], v[154:157], 0
	v_mfma_f32_16x16x32_bf16 v[10:13], v[244:247], v[184:187], 0
	v_mfma_f32_16x16x32_bf16 v[14:17], v[212:215], v[184:187], 0
	v_mfma_f32_16x16x32_bf16 v[2:5], v[244:247], v[236:239], 0
	v_mfma_f32_16x16x32_bf16 v[6:9], v[212:215], v[236:239], 0
	v_mfma_f32_16x16x32_bf16 v[26:29], v[248:251], v[150:153], v[26:29]
	v_mfma_f32_16x16x32_bf16 v[30:33], v[216:219], v[150:153], v[30:33]
	v_mfma_f32_16x16x32_bf16 v[18:21], v[248:251], v[158:161], v[18:21]
	v_mfma_f32_16x16x32_bf16 v[22:25], v[216:219], v[158:161], v[22:25]
	v_mfma_f32_16x16x32_bf16 v[10:13], v[248:251], v[204:207], v[10:13]
	v_mfma_f32_16x16x32_bf16 v[14:17], v[216:219], v[204:207], v[14:17]
	v_mfma_f32_16x16x32_bf16 v[2:5], v[248:251], v[240:243], v[2:5]
	v_mfma_f32_16x16x32_bf16 v[6:9], v[216:219], v[240:243], v[6:9]
	s_setprio 0
	s_add_i32 s29, 0, 0x18000
	v_add_u32_e32 v0, s29, v188
	s_barrier
	ds_read_b128 v[130:133], v0
	ds_read_b128 v[134:137], v0 offset:1024
	ds_read_b128 v[138:141], v0 offset:2048
	ds_read_b128 v[142:145], v0 offset:3072
	s_add_u32 s16, s16, 0x40000
	s_addc_u32 s17, s17, 0
	s_mov_b32 m0, s61
	v_lshl_add_u64 v[236:237], s[16:17], 0, v[162:163]
	ds_read_b128 v[146:149], v203 offset:32768
	ds_read_b128 v[150:153], v203 offset:33792
	ds_read_b128 v[154:157], v203 offset:34816
	ds_read_b128 v[158:161], v203 offset:35840
	ds_read_b128 v[184:187], v203 offset:36864
	ds_read_b128 v[204:207], v203 offset:37888
	ds_read_b128 v[212:215], v203 offset:38912
	ds_read_b128 v[216:219], v203 offset:39936
	global_load_lds_dwordx4 v[236:237], off
	v_lshl_add_u64 v[236:237], s[16:17], 0, v[166:167]
	s_mov_b32 m0, s38
	s_nop 0
	global_load_lds_dwordx4 v[236:237], off
	s_waitcnt lgkmcnt(8)
	s_barrier
	s_waitcnt lgkmcnt(0)
	s_setprio 1
	s_waitcnt lgkmcnt(0)
	v_mfma_f32_16x16x32_bf16 v[122:125], v[130:133], v[146:149], v[122:125]
	v_mfma_f32_16x16x32_bf16 v[126:129], v[138:141], v[146:149], v[126:129]
	v_mfma_f32_16x16x32_bf16 v[114:117], v[130:133], v[154:157], v[114:117]
	v_mfma_f32_16x16x32_bf16 v[118:121], v[138:141], v[154:157], v[118:121]
	v_mfma_f32_16x16x32_bf16 v[106:109], v[130:133], v[184:187], v[106:109]
	v_mfma_f32_16x16x32_bf16 v[110:113], v[138:141], v[184:187], v[110:113]
	v_mfma_f32_16x16x32_bf16 v[98:101], v[130:133], v[212:215], v[98:101]
	v_mfma_f32_16x16x32_bf16 v[102:105], v[138:141], v[212:215], v[102:105]
	v_mfma_f32_16x16x32_bf16 v[122:125], v[134:137], v[150:153], v[122:125]
	v_mfma_f32_16x16x32_bf16 v[126:129], v[142:145], v[150:153], v[126:129]
	v_mfma_f32_16x16x32_bf16 v[114:117], v[134:137], v[158:161], v[114:117]
	v_mfma_f32_16x16x32_bf16 v[118:121], v[142:145], v[158:161], v[118:121]
	v_mfma_f32_16x16x32_bf16 v[106:109], v[134:137], v[204:207], v[106:109]
	v_mfma_f32_16x16x32_bf16 v[110:113], v[142:145], v[204:207], v[110:113]
	v_mfma_f32_16x16x32_bf16 v[98:101], v[134:137], v[216:219], v[98:101]
	v_mfma_f32_16x16x32_bf16 v[102:105], v[142:145], v[216:219], v[102:105]
	s_setprio 0
	s_barrier
	s_add_i32 s16, 0, 0x1c000
	s_add_i32 s17, s29, s64
	v_add_u32_e32 v0, s16, v188
	v_lshl_add_u64 v[208:209], v[208:209], 0, s[56:57]
	s_mov_b32 m0, s17
	ds_read_b128 v[236:239], v0
	ds_read_b128 v[240:243], v0 offset:1024
	ds_read_b128 v[244:247], v0 offset:2048
	ds_read_b128 v[248:251], v0 offset:3072
	global_load_lds_dwordx4 v[208:209], off
	v_lshl_add_u64 v[208:209], v[230:231], 0, s[56:57]
	s_add_i32 m0, s17, 0x2000
	s_nop 0
	global_load_lds_dwordx4 v[208:209], off
	s_barrier
	s_waitcnt lgkmcnt(0)
	s_setprio 1
	s_waitcnt lgkmcnt(0)
	v_mfma_f32_16x16x32_bf16 v[90:93], v[236:239], v[146:149], v[90:93]
	v_mfma_f32_16x16x32_bf16 v[94:97], v[244:247], v[146:149], v[94:97]
	v_mfma_f32_16x16x32_bf16 v[82:85], v[236:239], v[154:157], v[82:85]
	v_mfma_f32_16x16x32_bf16 v[86:89], v[244:247], v[154:157], v[86:89]
	v_mfma_f32_16x16x32_bf16 v[74:77], v[236:239], v[184:187], v[74:77]
	v_mfma_f32_16x16x32_bf16 v[78:81], v[244:247], v[184:187], v[78:81]
	v_mfma_f32_16x16x32_bf16 v[66:69], v[236:239], v[212:215], v[66:69]
	v_mfma_f32_16x16x32_bf16 v[70:73], v[244:247], v[212:215], v[70:73]
	v_mfma_f32_16x16x32_bf16 v[90:93], v[240:243], v[150:153], v[90:93]
	v_mfma_f32_16x16x32_bf16 v[94:97], v[248:251], v[150:153], v[94:97]
	v_mfma_f32_16x16x32_bf16 v[82:85], v[240:243], v[158:161], v[82:85]
	v_mfma_f32_16x16x32_bf16 v[86:89], v[248:251], v[158:161], v[86:89]
	v_mfma_f32_16x16x32_bf16 v[74:77], v[240:243], v[204:207], v[74:77]
	v_mfma_f32_16x16x32_bf16 v[78:81], v[248:251], v[204:207], v[78:81]
	v_mfma_f32_16x16x32_bf16 v[66:69], v[240:243], v[216:219], v[66:69]
	v_mfma_f32_16x16x32_bf16 v[70:73], v[248:251], v[216:219], v[70:73]
	s_setprio 0
	s_mov_b32 m0, s30
	v_lshl_add_u64 v[208:209], v[222:223], 0, s[56:57]
	s_barrier
	ds_read_b128 v[146:149], v203 offset:49152
	ds_read_b128 v[150:153], v203 offset:50176
	ds_read_b128 v[154:157], v203 offset:51200
	ds_read_b128 v[158:161], v203 offset:52224
	ds_read_b128 v[184:187], v203 offset:53248
	ds_read_b128 v[204:207], v203 offset:54272
	ds_read_b128 v[212:215], v203 offset:55296
	ds_read_b128 v[216:219], v203 offset:56320
	global_load_lds_dwordx4 v[208:209], off
	v_lshl_add_u64 v[208:209], v[232:233], 0, s[56:57]
	s_mov_b32 m0, s0
	s_nop 0
	global_load_lds_dwordx4 v[208:209], off
	s_barrier
	s_waitcnt lgkmcnt(0)
	s_setprio 1
	s_waitcnt lgkmcnt(0)
	v_mfma_f32_16x16x32_bf16 v[58:61], v[130:133], v[146:149], v[58:61]
	v_mfma_f32_16x16x32_bf16 v[62:65], v[138:141], v[146:149], v[62:65]
	v_mfma_f32_16x16x32_bf16 v[50:53], v[130:133], v[154:157], v[50:53]
	v_mfma_f32_16x16x32_bf16 v[54:57], v[138:141], v[154:157], v[54:57]
	v_mfma_f32_16x16x32_bf16 v[42:45], v[130:133], v[184:187], v[42:45]
	v_mfma_f32_16x16x32_bf16 v[46:49], v[138:141], v[184:187], v[46:49]
	v_mfma_f32_16x16x32_bf16 v[34:37], v[130:133], v[212:215], v[34:37]
	v_mfma_f32_16x16x32_bf16 v[38:41], v[138:141], v[212:215], v[38:41]
	v_mfma_f32_16x16x32_bf16 v[58:61], v[134:137], v[150:153], v[58:61]
	v_mfma_f32_16x16x32_bf16 v[62:65], v[142:145], v[150:153], v[62:65]
	v_mfma_f32_16x16x32_bf16 v[50:53], v[134:137], v[158:161], v[50:53]
	v_mfma_f32_16x16x32_bf16 v[54:57], v[142:145], v[158:161], v[54:57]
	v_mfma_f32_16x16x32_bf16 v[42:45], v[134:137], v[204:207], v[42:45]
	v_mfma_f32_16x16x32_bf16 v[46:49], v[142:145], v[204:207], v[46:49]
	v_mfma_f32_16x16x32_bf16 v[34:37], v[134:137], v[216:219], v[34:37]
	v_mfma_f32_16x16x32_bf16 v[38:41], v[142:145], v[216:219], v[38:41]
	s_setprio 0
	s_barrier
	s_add_u32 s14, s14, 0x40080
	s_addc_u32 s15, s15, 0
	s_add_i32 s16, s16, s64
	v_lshl_add_u64 v[130:131], s[14:15], 0, v[164:165]
	s_mov_b32 m0, s16
	s_nop 0
	global_load_lds_dwordx4 v[130:131], off
	v_lshl_add_u64 v[130:131], s[14:15], 0, v[168:169]
	s_add_i32 m0, s16, 0x2000
	s_nop 0
	global_load_lds_dwordx4 v[130:131], off
	s_waitcnt vmcnt(6)
	s_barrier
	s_setprio 1
	v_mfma_f32_16x16x32_bf16 v[26:29], v[236:239], v[146:149], v[26:29]
	v_mfma_f32_16x16x32_bf16 v[30:33], v[244:247], v[146:149], v[30:33]
	v_mfma_f32_16x16x32_bf16 v[18:21], v[236:239], v[154:157], v[18:21]
	v_mfma_f32_16x16x32_bf16 v[22:25], v[244:247], v[154:157], v[22:25]
	v_mfma_f32_16x16x32_bf16 v[10:13], v[236:239], v[184:187], v[10:13]
	v_mfma_f32_16x16x32_bf16 v[14:17], v[244:247], v[184:187], v[14:17]
	v_mfma_f32_16x16x32_bf16 v[2:5], v[236:239], v[212:215], v[2:5]
	v_mfma_f32_16x16x32_bf16 v[6:9], v[244:247], v[212:215], v[6:9]
	v_mfma_f32_16x16x32_bf16 v[26:29], v[240:243], v[150:153], v[26:29]
	v_mfma_f32_16x16x32_bf16 v[30:33], v[248:251], v[150:153], v[30:33]
	v_mfma_f32_16x16x32_bf16 v[18:21], v[240:243], v[158:161], v[18:21]
	v_mfma_f32_16x16x32_bf16 v[22:25], v[248:251], v[158:161], v[22:25]
	v_mfma_f32_16x16x32_bf16 v[10:13], v[240:243], v[204:207], v[10:13]
	v_mfma_f32_16x16x32_bf16 v[14:17], v[248:251], v[204:207], v[14:17]
	v_mfma_f32_16x16x32_bf16 v[2:5], v[240:243], v[216:219], v[2:5]
	v_mfma_f32_16x16x32_bf16 v[6:9], v[248:251], v[216:219], v[6:9]
	s_setprio 0
	s_add_i32 s28, s28, 2
	s_add_u32 s12, s12, 0x100
	s_addc_u32 s13, s13, 0
	s_add_u32 s22, s22, 0x100
	s_addc_u32 s23, s23, 0
	s_cmp_gt_u32 s28, 13
	s_barrier

.LBB0_521:
	s_ashr_i32 s7, s6, 31
	s_lshl_b64 s[16:17], s[6:7], 18
	s_add_u32 s16, s5, s16
	s_addc_u32 s17, s22, s17
	s_and_b64 s[8:9], s[8:9], exec
	s_cselect_b32 s7, s17, s13
	s_cselect_b32 s63, s16, s12
	s_add_u32 s64, s12, 0x100
	s_addc_u32 s65, s13, 0
	s_mov_b32 s72, -2
	s_add_u32 s8, s10, 0x100
	s_addc_u32 s9, s11, 0
	s_add_i32 s74, 0, 0x10000
	v_add_u32_e32 v142, s74, v236
	ds_read_b128 v[114:117], v142
	ds_read_b128 v[118:121], v142 offset:1024
	ds_read_b128 v[138:141], v142 offset:2048
	ds_read_b128 v[142:145], v142 offset:3072
	s_cmp_eq_u32 s72, 4
	s_cselect_b32 s19, s15, s9
	s_cselect_b32 s18, s14, s8
	s_cselect_b32 s13, s7, s65
	s_cselect_b32 s12, s63, s64
	v_lshl_add_u64 v[188:189], s[10:11], 0, v[184:185]
	s_add_i32 m0, s24, 0xc000
	ds_read_b128 v[146:149], v238
	ds_read_b128 v[150:153], v238 offset:1024
	ds_read_b128 v[154:157], v238 offset:2048
	ds_read_b128 v[158:161], v238 offset:3072
	ds_read_b128 v[162:165], v238 offset:4096
	ds_read_b128 v[166:169], v238 offset:5120
	ds_read_b128 v[170:173], v238 offset:6144
	ds_read_b128 v[174:177], v238 offset:7168
	global_load_lds_dwordx4 v[188:189], off
	v_lshl_add_u64 v[188:189], s[10:11], 0, v[186:187]
	s_add_i32 m0, s24, 0xe000
	s_nop 0
	global_load_lds_dwordx4 v[188:189], off
	s_waitcnt lgkmcnt(8)
	s_barrier
	s_waitcnt lgkmcnt(0)
	s_setprio 1
	s_waitcnt lgkmcnt(0)
	v_mfma_f32_16x16x32_bf16 v[134:137], v[114:117], v[146:149], 0
	v_mfma_f32_16x16x32_bf16 v[130:133], v[138:141], v[146:149], 0
	v_mfma_f32_16x16x32_bf16 v[110:113], v[114:117], v[154:157], 0
	v_mfma_f32_16x16x32_bf16 v[106:109], v[138:141], v[154:157], 0
	v_mfma_f32_16x16x32_bf16 v[94:97], v[114:117], v[162:165], 0
	v_mfma_f32_16x16x32_bf16 v[90:93], v[138:141], v[162:165], 0
	v_mfma_f32_16x16x32_bf16 v[78:81], v[114:117], v[170:173], 0
	v_mfma_f32_16x16x32_bf16 v[74:77], v[138:141], v[170:173], 0
	v_mfma_f32_16x16x32_bf16 v[134:137], v[118:121], v[150:153], v[134:137]
	v_mfma_f32_16x16x32_bf16 v[130:133], v[142:145], v[150:153], v[130:133]
	v_mfma_f32_16x16x32_bf16 v[110:113], v[118:121], v[158:161], v[110:113]
	v_mfma_f32_16x16x32_bf16 v[106:109], v[142:145], v[158:161], v[106:109]
	v_mfma_f32_16x16x32_bf16 v[94:97], v[118:121], v[166:169], v[94:97]
	v_mfma_f32_16x16x32_bf16 v[90:93], v[142:145], v[166:169], v[90:93]
	v_mfma_f32_16x16x32_bf16 v[78:81], v[118:121], v[174:177], v[78:81]
	v_mfma_f32_16x16x32_bf16 v[74:77], v[142:145], v[174:177], v[74:77]
	s_setprio 0
	s_barrier
	s_add_i32 s75, 0, 0x14000
	s_add_i32 s10, s74, s23
	v_add_u32_e32 v200, s75, v236
	v_lshl_add_u64 v[204:205], s[12:13], 0, v[0:1]
	s_mov_b32 m0, s10
	ds_read_b128 v[188:191], v200
	ds_read_b128 v[192:195], v200 offset:1024
	ds_read_b128 v[196:199], v200 offset:2048
	ds_read_b128 v[200:203], v200 offset:3072
	global_load_lds_dwordx4 v[204:205], off
	v_lshl_add_u64 v[206:207], s[12:13], 0, v[178:179]
	s_add_i32 m0, s10, 0x2000
	s_nop 0
	global_load_lds_dwordx4 v[206:207], off
	s_barrier
	s_waitcnt lgkmcnt(0)
	s_setprio 1
	s_waitcnt lgkmcnt(0)
	v_mfma_f32_16x16x32_bf16 v[126:129], v[188:191], v[146:149], 0
	v_mfma_f32_16x16x32_bf16 v[122:125], v[196:199], v[146:149], 0
	v_mfma_f32_16x16x32_bf16 v[102:105], v[188:191], v[154:157], 0
	v_mfma_f32_16x16x32_bf16 v[98:101], v[196:199], v[154:157], 0
	v_mfma_f32_16x16x32_bf16 v[86:89], v[188:191], v[162:165], 0
	v_mfma_f32_16x16x32_bf16 v[82:85], v[196:199], v[162:165], 0
	v_mfma_f32_16x16x32_bf16 v[70:73], v[188:191], v[170:173], 0
	v_mfma_f32_16x16x32_bf16 v[66:69], v[196:199], v[170:173], 0
	v_mfma_f32_16x16x32_bf16 v[126:129], v[192:195], v[150:153], v[126:129]
	v_mfma_f32_16x16x32_bf16 v[122:125], v[200:203], v[150:153], v[122:125]
	v_mfma_f32_16x16x32_bf16 v[102:105], v[192:195], v[158:161], v[102:105]
	v_mfma_f32_16x16x32_bf16 v[98:101], v[200:203], v[158:161], v[98:101]
	v_mfma_f32_16x16x32_bf16 v[86:89], v[192:195], v[166:169], v[86:89]
	v_mfma_f32_16x16x32_bf16 v[82:85], v[200:203], v[166:169], v[82:85]
	v_mfma_f32_16x16x32_bf16 v[70:73], v[192:195], v[174:177], v[70:73]
	v_mfma_f32_16x16x32_bf16 v[66:69], v[200:203], v[174:177], v[66:69]
	s_setprio 0
	s_mov_b32 m0, s24
	v_lshl_add_u64 v[208:209], s[18:19], 0, v[182:183]
	s_barrier
	ds_read_b128 v[146:149], v238 offset:16384
	ds_read_b128 v[150:153], v238 offset:17408
	ds_read_b128 v[154:157], v238 offset:18432
	ds_read_b128 v[158:161], v238 offset:19456
	ds_read_b128 v[162:165], v238 offset:20480
	ds_read_b128 v[166:169], v238 offset:21504
	ds_read_b128 v[170:173], v238 offset:22528
	ds_read_b128 v[174:177], v238 offset:23552
	global_load_lds_dwordx4 v[208:209], off
	v_lshl_add_u64 v[212:213], s[18:19], 0, v[180:181]
	s_mov_b32 m0, s25
	s_nop 0
	global_load_lds_dwordx4 v[212:213], off
	s_barrier
	s_waitcnt lgkmcnt(0)
	s_setprio 1
	s_waitcnt lgkmcnt(0)
	v_mfma_f32_16x16x32_bf16 v[62:65], v[114:117], v[146:149], 0
	v_mfma_f32_16x16x32_bf16 v[58:61], v[138:141], v[146:149], 0
	v_mfma_f32_16x16x32_bf16 v[46:49], v[114:117], v[154:157], 0
	v_mfma_f32_16x16x32_bf16 v[42:45], v[138:141], v[154:157], 0
	v_mfma_f32_16x16x32_bf16 v[30:33], v[114:117], v[162:165], 0
	v_mfma_f32_16x16x32_bf16 v[26:29], v[138:141], v[162:165], 0
	v_mfma_f32_16x16x32_bf16 v[14:17], v[114:117], v[170:173], 0
	v_mfma_f32_16x16x32_bf16 v[10:13], v[138:141], v[170:173], 0
	v_mfma_f32_16x16x32_bf16 v[62:65], v[118:121], v[150:153], v[62:65]
	v_mfma_f32_16x16x32_bf16 v[58:61], v[142:145], v[150:153], v[58:61]
	v_mfma_f32_16x16x32_bf16 v[46:49], v[118:121], v[158:161], v[46:49]
	v_mfma_f32_16x16x32_bf16 v[42:45], v[142:145], v[158:161], v[42:45]
	v_mfma_f32_16x16x32_bf16 v[30:33], v[118:121], v[166:169], v[30:33]
	v_mfma_f32_16x16x32_bf16 v[26:29], v[142:145], v[166:169], v[26:29]
	v_mfma_f32_16x16x32_bf16 v[14:17], v[118:121], v[174:177], v[14:17]
	v_mfma_f32_16x16x32_bf16 v[10:13], v[142:145], v[174:177], v[10:13]
	s_setprio 0
	s_barrier
	s_add_u32 s10, s12, 0x20000
	s_addc_u32 s11, s13, 0
	s_add_i32 s74, s75, s23
	v_lshl_add_u64 v[114:115], s[10:11], 0, v[0:1]
	s_mov_b32 m0, s74
	s_nop 0
	global_load_lds_dwordx4 v[114:115], off
	v_lshl_add_u64 v[114:115], s[10:11], 0, v[178:179]
	s_add_i32 m0, s74, 0x2000
	s_nop 0
	global_load_lds_dwordx4 v[114:115], off
	s_waitcnt vmcnt(6)
	s_barrier
	s_setprio 1
	v_mfma_f32_16x16x32_bf16 v[54:57], v[188:191], v[146:149], 0
	v_mfma_f32_16x16x32_bf16 v[50:53], v[196:199], v[146:149], 0
	v_mfma_f32_16x16x32_bf16 v[38:41], v[188:191], v[154:157], 0
	v_mfma_f32_16x16x32_bf16 v[34:37], v[196:199], v[154:157], 0
	v_mfma_f32_16x16x32_bf16 v[22:25], v[188:191], v[162:165], 0
	v_mfma_f32_16x16x32_bf16 v[18:21], v[196:199], v[162:165], 0
	v_mfma_f32_16x16x32_bf16 v[6:9], v[188:191], v[170:173], 0
	v_mfma_f32_16x16x32_bf16 v[2:5], v[196:199], v[170:173], 0
	v_mfma_f32_16x16x32_bf16 v[54:57], v[192:195], v[150:153], v[54:57]
	v_mfma_f32_16x16x32_bf16 v[50:53], v[200:203], v[150:153], v[50:53]
	v_mfma_f32_16x16x32_bf16 v[38:41], v[192:195], v[158:161], v[38:41]
	v_mfma_f32_16x16x32_bf16 v[34:37], v[200:203], v[158:161], v[34:37]
	v_mfma_f32_16x16x32_bf16 v[22:25], v[192:195], v[166:169], v[22:25]
	v_mfma_f32_16x16x32_bf16 v[18:21], v[200:203], v[166:169], v[18:21]
	v_mfma_f32_16x16x32_bf16 v[6:9], v[192:195], v[174:177], v[6:9]
	v_mfma_f32_16x16x32_bf16 v[2:5], v[200:203], v[174:177], v[2:5]
	s_setprio 0
	s_add_i32 s74, 0, 0x18000
	v_add_u32_e32 v142, s74, v236
	s_barrier
	ds_read_b128 v[114:117], v142
	ds_read_b128 v[118:121], v142 offset:1024
	ds_read_b128 v[138:141], v142 offset:2048
	ds_read_b128 v[142:145], v142 offset:3072
	s_add_u32 s10, s18, 0x7a000
	s_addc_u32 s11, s19, 0
	s_mov_b32 m0, s28
	v_lshl_add_u64 v[188:189], s[10:11], 0, v[182:183]
	ds_read_b128 v[146:149], v238 offset:32768
	ds_read_b128 v[150:153], v238 offset:33792
	ds_read_b128 v[154:157], v238 offset:34816
	ds_read_b128 v[158:161], v238 offset:35840
	ds_read_b128 v[162:165], v238 offset:36864
	ds_read_b128 v[166:169], v238 offset:37888
	ds_read_b128 v[170:173], v238 offset:38912
	ds_read_b128 v[174:177], v238 offset:39936
	global_load_lds_dwordx4 v[188:189], off
	v_lshl_add_u64 v[188:189], s[10:11], 0, v[180:181]
	s_mov_b32 m0, s29
	s_nop 0
	global_load_lds_dwordx4 v[188:189], off
	s_waitcnt lgkmcnt(8)
	s_barrier
	s_waitcnt lgkmcnt(0)
	s_setprio 1
	s_waitcnt lgkmcnt(0)
	v_mfma_f32_16x16x32_bf16 v[134:137], v[114:117], v[146:149], v[134:137]
	v_mfma_f32_16x16x32_bf16 v[130:133], v[138:141], v[146:149], v[130:133]
	v_mfma_f32_16x16x32_bf16 v[110:113], v[114:117], v[154:157], v[110:113]
	v_mfma_f32_16x16x32_bf16 v[106:109], v[138:141], v[154:157], v[106:109]
	v_mfma_f32_16x16x32_bf16 v[94:97], v[114:117], v[162:165], v[94:97]
	v_mfma_f32_16x16x32_bf16 v[90:93], v[138:141], v[162:165], v[90:93]
	v_mfma_f32_16x16x32_bf16 v[78:81], v[114:117], v[170:173], v[78:81]
	v_mfma_f32_16x16x32_bf16 v[74:77], v[138:141], v[170:173], v[74:77]
	v_mfma_f32_16x16x32_bf16 v[134:137], v[118:121], v[150:153], v[134:137]
	v_mfma_f32_16x16x32_bf16 v[130:133], v[142:145], v[150:153], v[130:133]
	v_mfma_f32_16x16x32_bf16 v[110:113], v[118:121], v[158:161], v[110:113]
	v_mfma_f32_16x16x32_bf16 v[106:109], v[142:145], v[158:161], v[106:109]
	v_mfma_f32_16x16x32_bf16 v[94:97], v[118:121], v[166:169], v[94:97]
	v_mfma_f32_16x16x32_bf16 v[90:93], v[142:145], v[166:169], v[90:93]
	v_mfma_f32_16x16x32_bf16 v[78:81], v[118:121], v[174:177], v[78:81]
	v_mfma_f32_16x16x32_bf16 v[74:77], v[142:145], v[174:177], v[74:77]
	s_setprio 0
	s_barrier
	s_add_i32 s18, 0, 0x1c000
	s_add_i32 s10, s74, s23
	v_add_u32_e32 v200, s18, v236
	v_lshl_add_u64 v[204:205], v[204:205], 0, s[56:57]
	s_mov_b32 m0, s10
	ds_read_b128 v[188:191], v200
	ds_read_b128 v[192:195], v200 offset:1024
	ds_read_b128 v[196:199], v200 offset:2048
	ds_read_b128 v[200:203], v200 offset:3072
	global_load_lds_dwordx4 v[204:205], off
	v_lshl_add_u64 v[204:205], v[206:207], 0, s[56:57]
	s_add_i32 m0, s10, 0x2000
	s_nop 0
	global_load_lds_dwordx4 v[204:205], off
	s_barrier
	s_waitcnt lgkmcnt(0)
	s_setprio 1
	s_waitcnt lgkmcnt(0)
	v_mfma_f32_16x16x32_bf16 v[126:129], v[188:191], v[146:149], v[126:129]
	v_mfma_f32_16x16x32_bf16 v[122:125], v[196:199], v[146:149], v[122:125]
	v_mfma_f32_16x16x32_bf16 v[102:105], v[188:191], v[154:157], v[102:105]
	v_mfma_f32_16x16x32_bf16 v[98:101], v[196:199], v[154:157], v[98:101]
	v_mfma_f32_16x16x32_bf16 v[86:89], v[188:191], v[162:165], v[86:89]
	v_mfma_f32_16x16x32_bf16 v[82:85], v[196:199], v[162:165], v[82:85]
	v_mfma_f32_16x16x32_bf16 v[70:73], v[188:191], v[170:173], v[70:73]
	v_mfma_f32_16x16x32_bf16 v[66:69], v[196:199], v[170:173], v[66:69]
	v_mfma_f32_16x16x32_bf16 v[126:129], v[192:195], v[150:153], v[126:129]
	v_mfma_f32_16x16x32_bf16 v[122:125], v[200:203], v[150:153], v[122:125]
	v_mfma_f32_16x16x32_bf16 v[102:105], v[192:195], v[158:161], v[102:105]
	v_mfma_f32_16x16x32_bf16 v[98:101], v[200:203], v[158:161], v[98:101]
	v_mfma_f32_16x16x32_bf16 v[86:89], v[192:195], v[166:169], v[86:89]
	v_mfma_f32_16x16x32_bf16 v[82:85], v[200:203], v[166:169], v[82:85]
	v_mfma_f32_16x16x32_bf16 v[70:73], v[192:195], v[174:177], v[70:73]
	v_mfma_f32_16x16x32_bf16 v[66:69], v[200:203], v[174:177], v[66:69]
	s_setprio 0
	s_mov_b32 m0, s34
	v_lshl_add_u64 v[204:205], v[208:209], 0, s[56:57]
	s_barrier
	ds_read_b128 v[146:149], v238 offset:49152
	ds_read_b128 v[150:153], v238 offset:50176
	ds_read_b128 v[154:157], v238 offset:51200
	ds_read_b128 v[158:161], v238 offset:52224
	ds_read_b128 v[162:165], v238 offset:53248
	ds_read_b128 v[166:169], v238 offset:54272
	ds_read_b128 v[170:173], v238 offset:55296
	ds_read_b128 v[174:177], v238 offset:56320
	global_load_lds_dwordx4 v[204:205], off
	v_lshl_add_u64 v[204:205], v[212:213], 0, s[56:57]
	s_mov_b32 m0, s35
	s_nop 0
	global_load_lds_dwordx4 v[204:205], off
	s_barrier
	s_waitcnt lgkmcnt(0)
	s_setprio 1
	s_waitcnt lgkmcnt(0)
	v_mfma_f32_16x16x32_bf16 v[62:65], v[114:117], v[146:149], v[62:65]
	v_mfma_f32_16x16x32_bf16 v[58:61], v[138:141], v[146:149], v[58:61]
	v_mfma_f32_16x16x32_bf16 v[46:49], v[114:117], v[154:157], v[46:49]
	v_mfma_f32_16x16x32_bf16 v[42:45], v[138:141], v[154:157], v[42:45]
	v_mfma_f32_16x16x32_bf16 v[30:33], v[114:117], v[162:165], v[30:33]
	v_mfma_f32_16x16x32_bf16 v[26:29], v[138:141], v[162:165], v[26:29]
	v_mfma_f32_16x16x32_bf16 v[14:17], v[114:117], v[170:173], v[14:17]
	v_mfma_f32_16x16x32_bf16 v[10:13], v[138:141], v[170:173], v[10:13]
	v_mfma_f32_16x16x32_bf16 v[62:65], v[118:121], v[150:153], v[62:65]
	v_mfma_f32_16x16x32_bf16 v[58:61], v[142:145], v[150:153], v[58:61]
	v_mfma_f32_16x16x32_bf16 v[46:49], v[118:121], v[158:161], v[46:49]
	v_mfma_f32_16x16x32_bf16 v[42:45], v[142:145], v[158:161], v[42:45]
	v_mfma_f32_16x16x32_bf16 v[30:33], v[118:121], v[166:169], v[30:33]
	v_mfma_f32_16x16x32_bf16 v[26:29], v[142:145], v[166:169], v[26:29]
	v_mfma_f32_16x16x32_bf16 v[14:17], v[118:121], v[174:177], v[14:17]
	v_mfma_f32_16x16x32_bf16 v[10:13], v[142:145], v[174:177], v[10:13]
	s_setprio 0
	s_barrier
	s_add_u32 s10, s12, 0x20080
	s_addc_u32 s11, s13, 0
	s_add_i32 s12, s18, s23
	v_lshl_add_u64 v[114:115], s[10:11], 0, v[0:1]
	s_mov_b32 m0, s12
	s_nop 0
	global_load_lds_dwordx4 v[114:115], off
	v_lshl_add_u64 v[114:115], s[10:11], 0, v[178:179]
	s_add_i32 m0, s12, 0x2000
	s_nop 0
	global_load_lds_dwordx4 v[114:115], off
	s_waitcnt vmcnt(6)
	s_barrier
	s_setprio 1
	v_mfma_f32_16x16x32_bf16 v[54:57], v[188:191], v[146:149], v[54:57]
	v_mfma_f32_16x16x32_bf16 v[50:53], v[196:199], v[146:149], v[50:53]
	v_mfma_f32_16x16x32_bf16 v[38:41], v[188:191], v[154:157], v[38:41]
	v_mfma_f32_16x16x32_bf16 v[34:37], v[196:199], v[154:157], v[34:37]
	v_mfma_f32_16x16x32_bf16 v[22:25], v[188:191], v[162:165], v[22:25]
	v_mfma_f32_16x16x32_bf16 v[18:21], v[196:199], v[162:165], v[18:21]
	v_mfma_f32_16x16x32_bf16 v[6:9], v[188:191], v[170:173], v[6:9]
	v_mfma_f32_16x16x32_bf16 v[2:5], v[196:199], v[170:173], v[2:5]
	v_mfma_f32_16x16x32_bf16 v[54:57], v[192:195], v[150:153], v[54:57]
	v_mfma_f32_16x16x32_bf16 v[50:53], v[200:203], v[150:153], v[50:53]
	v_mfma_f32_16x16x32_bf16 v[38:41], v[192:195], v[158:161], v[38:41]
	v_mfma_f32_16x16x32_bf16 v[34:37], v[200:203], v[158:161], v[34:37]
	v_mfma_f32_16x16x32_bf16 v[22:25], v[192:195], v[166:169], v[22:25]
	v_mfma_f32_16x16x32_bf16 v[18:21], v[200:203], v[166:169], v[18:21]
	v_mfma_f32_16x16x32_bf16 v[6:9], v[192:195], v[174:177], v[6:9]
	v_mfma_f32_16x16x32_bf16 v[2:5], v[200:203], v[174:177], v[2:5]
	s_setprio 0
	s_add_i32 s72, s72, 2
	s_add_u32 s64, s64, 0x100
	s_addc_u32 s65, s65, 0
	s_cmp_gt_u32 s72, 5
	s_mov_b64 s[10:11], s[8:9]
	s_barrier

.LBB0_1074:
	v_readlane_b32 s36, v252, 0
	v_readlane_b32 s37, v252, 1
	s_ashr_i32 s11, s10, 31
	v_readlane_b32 s14, v254, 59
	v_mov_b64_e32 v[2:3], s[36:37]
	v_cmp_lt_i64_e32 vcc, s[12:13], v[2:3]
	s_lshl_b64 s[12:13], s[10:11], 19
	v_readlane_b32 s15, v254, 60
	s_add_u32 s12, s14, s12
	s_addc_u32 s13, s15, s13
	s_and_b64 s[14:15], vcc, exec
	s_cselect_b32 s11, s13, s21
	s_cselect_b32 s17, s12, s20
	s_ashr_i32 s7, s6, 31
	s_lshl_b64 s[14:15], s[6:7], 19
	s_add_u32 s14, s61, s14
	s_addc_u32 s15, s62, s15
	s_and_b64 s[28:29], vcc, exec
	s_cselect_b32 s7, s15, s23
	s_cselect_b32 s34, s14, s22
	s_add_u32 s20, s20, 0x40080
	s_addc_u32 s21, s21, 0
	s_add_u32 s35, s22, 0x100
	s_addc_u32 s82, s23, 0
	s_mov_b32 s83, -2
	v_readlane_b32 s38, v252, 2
	v_readlane_b32 s39, v252, 3
	v_readlane_b32 s40, v252, 4
	v_readlane_b32 s41, v252, 5
	v_readlane_b32 s42, v252, 6
	v_readlane_b32 s43, v252, 7
	v_readlane_b32 s44, v252, 8
	v_readlane_b32 s45, v252, 9
	v_readlane_b32 s46, v252, 10
	v_readlane_b32 s47, v252, 11
	v_readlane_b32 s48, v252, 12
	v_readlane_b32 s49, v252, 13
	v_readlane_b32 s50, v252, 14
	v_readlane_b32 s51, v252, 15
	s_add_u32 s22, s20, 0xfffc0080
	s_addc_u32 s23, s21, -1
	s_add_i32 s84, 0, 0x10000
	s_waitcnt vmcnt(0)
	v_add_u32_e32 v134, s84, v189
	ds_read_b128 v[122:125], v134
	ds_read_b128 v[126:129], v134 offset:1024
	ds_read_b128 v[130:133], v134 offset:2048
	ds_read_b128 v[134:137], v134 offset:3072
	s_cmp_eq_u32 s83, 12
	s_cselect_b32 s29, s11, s23
	s_cselect_b32 s28, s17, s22
	s_cselect_b32 s23, s7, s82
	s_cselect_b32 s22, s34, s35
	v_lshl_add_u64 v[192:193], s[20:21], 0, v[172:173]
	s_add_i32 m0, s19, 0xc000
	ds_read_b128 v[146:149], v191
	ds_read_b128 v[150:153], v191 offset:1024
	ds_read_b128 v[154:157], v191 offset:2048
	ds_read_b128 v[158:161], v191 offset:3072
	ds_read_b128 v[162:165], v191 offset:4096
	ds_read_b128 v[176:179], v191 offset:5120
	ds_read_b128 v[180:183], v191 offset:6144
	ds_read_b128 v[184:187], v191 offset:7168
	global_load_lds_dwordx4 v[192:193], off
	v_lshl_add_u64 v[192:193], s[20:21], 0, v[174:175]
	s_add_i32 m0, s19, 0xe000
	s_nop 0
	global_load_lds_dwordx4 v[192:193], off
	s_waitcnt lgkmcnt(8)
	s_barrier
	s_waitcnt lgkmcnt(0)
	s_setprio 1
	s_waitcnt lgkmcnt(0)
	v_mfma_f32_16x16x32_bf16 v[142:145], v[122:125], v[146:149], 0
	v_mfma_f32_16x16x32_bf16 v[138:141], v[130:133], v[146:149], 0
	v_mfma_f32_16x16x32_bf16 v[110:113], v[122:125], v[154:157], 0
	v_mfma_f32_16x16x32_bf16 v[106:109], v[130:133], v[154:157], 0
	v_mfma_f32_16x16x32_bf16 v[94:97], v[122:125], v[162:165], 0
	v_mfma_f32_16x16x32_bf16 v[90:93], v[130:133], v[162:165], 0
	v_mfma_f32_16x16x32_bf16 v[78:81], v[122:125], v[180:183], 0
	v_mfma_f32_16x16x32_bf16 v[74:77], v[130:133], v[180:183], 0
	v_mfma_f32_16x16x32_bf16 v[142:145], v[126:129], v[150:153], v[142:145]
	v_mfma_f32_16x16x32_bf16 v[138:141], v[134:137], v[150:153], v[138:141]
	v_mfma_f32_16x16x32_bf16 v[110:113], v[126:129], v[158:161], v[110:113]
	v_mfma_f32_16x16x32_bf16 v[106:109], v[134:137], v[158:161], v[106:109]
	v_mfma_f32_16x16x32_bf16 v[94:97], v[126:129], v[176:179], v[94:97]
	v_mfma_f32_16x16x32_bf16 v[90:93], v[134:137], v[176:179], v[90:93]
	v_mfma_f32_16x16x32_bf16 v[78:81], v[126:129], v[184:187], v[78:81]
	v_mfma_f32_16x16x32_bf16 v[74:77], v[134:137], v[184:187], v[74:77]
	s_setprio 0
	s_barrier
	s_add_i32 s86, 0, 0x14000
	s_add_i32 s84, s84, s63
	v_add_u32_e32 v204, s86, v189
	v_lshl_add_u64 v[208:209], s[22:23], 0, v[0:1]
	s_mov_b32 m0, s84
	ds_read_b128 v[192:195], v204
	ds_read_b128 v[196:199], v204 offset:1024
	ds_read_b128 v[200:203], v204 offset:2048
	ds_read_b128 v[204:207], v204 offset:3072
	global_load_lds_dwordx4 v[208:209], off
	v_lshl_add_u64 v[212:213], s[22:23], 0, v[170:171]
	s_add_i32 m0, s84, 0x2000
	s_nop 0
	global_load_lds_dwordx4 v[212:213], off
	s_barrier
	s_waitcnt lgkmcnt(0)
	s_setprio 1
	s_waitcnt lgkmcnt(0)
	v_mfma_f32_16x16x32_bf16 v[118:121], v[192:195], v[146:149], 0
	v_mfma_f32_16x16x32_bf16 v[114:117], v[200:203], v[146:149], 0
	v_mfma_f32_16x16x32_bf16 v[102:105], v[192:195], v[154:157], 0
	v_mfma_f32_16x16x32_bf16 v[98:101], v[200:203], v[154:157], 0
	v_mfma_f32_16x16x32_bf16 v[86:89], v[192:195], v[162:165], 0
	v_mfma_f32_16x16x32_bf16 v[82:85], v[200:203], v[162:165], 0
	v_mfma_f32_16x16x32_bf16 v[70:73], v[192:195], v[180:183], 0
	v_mfma_f32_16x16x32_bf16 v[66:69], v[200:203], v[180:183], 0
	v_mfma_f32_16x16x32_bf16 v[118:121], v[196:199], v[150:153], v[118:121]
	v_mfma_f32_16x16x32_bf16 v[114:117], v[204:207], v[150:153], v[114:117]
	v_mfma_f32_16x16x32_bf16 v[102:105], v[196:199], v[158:161], v[102:105]
	v_mfma_f32_16x16x32_bf16 v[98:101], v[204:207], v[158:161], v[98:101]
	v_mfma_f32_16x16x32_bf16 v[86:89], v[196:199], v[176:179], v[86:89]
	v_mfma_f32_16x16x32_bf16 v[82:85], v[204:207], v[176:179], v[82:85]
	v_mfma_f32_16x16x32_bf16 v[70:73], v[196:199], v[184:187], v[70:73]
	v_mfma_f32_16x16x32_bf16 v[66:69], v[204:207], v[184:187], v[66:69]
	s_setprio 0
	s_mov_b32 m0, s19
	v_lshl_add_u64 v[214:215], s[28:29], 0, v[166:167]
	s_barrier
	ds_read_b128 v[146:149], v191 offset:16384
	ds_read_b128 v[150:153], v191 offset:17408
	ds_read_b128 v[154:157], v191 offset:18432
	ds_read_b128 v[158:161], v191 offset:19456
	ds_read_b128 v[162:165], v191 offset:20480
	ds_read_b128 v[176:179], v191 offset:21504
	ds_read_b128 v[180:183], v191 offset:22528
	ds_read_b128 v[184:187], v191 offset:23552
	global_load_lds_dwordx4 v[214:215], off
	v_lshl_add_u64 v[216:217], s[28:29], 0, v[168:169]
	s_mov_b32 m0, s64
	s_nop 0
	global_load_lds_dwordx4 v[216:217], off
	s_barrier
	s_waitcnt lgkmcnt(0)
	s_setprio 1
	s_waitcnt lgkmcnt(0)
	v_mfma_f32_16x16x32_bf16 v[62:65], v[122:125], v[146:149], 0
	v_mfma_f32_16x16x32_bf16 v[58:61], v[130:133], v[146:149], 0
	v_mfma_f32_16x16x32_bf16 v[46:49], v[122:125], v[154:157], 0
	v_mfma_f32_16x16x32_bf16 v[42:45], v[130:133], v[154:157], 0
	v_mfma_f32_16x16x32_bf16 v[30:33], v[122:125], v[162:165], 0
	v_mfma_f32_16x16x32_bf16 v[26:29], v[130:133], v[162:165], 0
	v_mfma_f32_16x16x32_bf16 v[14:17], v[122:125], v[180:183], 0
	v_mfma_f32_16x16x32_bf16 v[10:13], v[130:133], v[180:183], 0
	v_mfma_f32_16x16x32_bf16 v[62:65], v[126:129], v[150:153], v[62:65]
	v_mfma_f32_16x16x32_bf16 v[58:61], v[134:137], v[150:153], v[58:61]
	v_mfma_f32_16x16x32_bf16 v[46:49], v[126:129], v[158:161], v[46:49]
	v_mfma_f32_16x16x32_bf16 v[42:45], v[134:137], v[158:161], v[42:45]
	v_mfma_f32_16x16x32_bf16 v[30:33], v[126:129], v[176:179], v[30:33]
	v_mfma_f32_16x16x32_bf16 v[26:29], v[134:137], v[176:179], v[26:29]
	v_mfma_f32_16x16x32_bf16 v[14:17], v[126:129], v[184:187], v[14:17]
	v_mfma_f32_16x16x32_bf16 v[10:13], v[134:137], v[184:187], v[10:13]
	s_setprio 0
	s_barrier
	s_add_u32 s84, s22, 0x40000
	s_addc_u32 s85, s23, 0
	s_add_i32 s86, s86, s63
	v_lshl_add_u64 v[122:123], s[84:85], 0, v[0:1]
	s_mov_b32 m0, s86
	s_nop 0
	global_load_lds_dwordx4 v[122:123], off
	v_lshl_add_u64 v[122:123], s[84:85], 0, v[170:171]
	s_add_i32 m0, s86, 0x2000
	s_nop 0
	global_load_lds_dwordx4 v[122:123], off
	s_waitcnt vmcnt(6)
	s_barrier
	s_setprio 1
	v_mfma_f32_16x16x32_bf16 v[54:57], v[192:195], v[146:149], 0
	v_mfma_f32_16x16x32_bf16 v[50:53], v[200:203], v[146:149], 0
	v_mfma_f32_16x16x32_bf16 v[38:41], v[192:195], v[154:157], 0
	v_mfma_f32_16x16x32_bf16 v[34:37], v[200:203], v[154:157], 0
	v_mfma_f32_16x16x32_bf16 v[22:25], v[192:195], v[162:165], 0
	v_mfma_f32_16x16x32_bf16 v[18:21], v[200:203], v[162:165], 0
	v_mfma_f32_16x16x32_bf16 v[6:9], v[192:195], v[180:183], 0
	v_mfma_f32_16x16x32_bf16 v[2:5], v[200:203], v[180:183], 0
	v_mfma_f32_16x16x32_bf16 v[54:57], v[196:199], v[150:153], v[54:57]
	v_mfma_f32_16x16x32_bf16 v[50:53], v[204:207], v[150:153], v[50:53]
	v_mfma_f32_16x16x32_bf16 v[38:41], v[196:199], v[158:161], v[38:41]
	v_mfma_f32_16x16x32_bf16 v[34:37], v[204:207], v[158:161], v[34:37]
	v_mfma_f32_16x16x32_bf16 v[22:25], v[196:199], v[176:179], v[22:25]
	v_mfma_f32_16x16x32_bf16 v[18:21], v[204:207], v[176:179], v[18:21]
	v_mfma_f32_16x16x32_bf16 v[6:9], v[196:199], v[184:187], v[6:9]
	v_mfma_f32_16x16x32_bf16 v[2:5], v[204:207], v[184:187], v[2:5]
	s_setprio 0
	s_add_i32 s84, 0, 0x18000
	v_add_u32_e32 v134, s84, v189
	s_barrier
	ds_read_b128 v[122:125], v134
	ds_read_b128 v[126:129], v134 offset:1024
	ds_read_b128 v[130:133], v134 offset:2048
	ds_read_b128 v[134:137], v134 offset:3072
	s_add_u32 s28, s28, 0x40000
	s_addc_u32 s29, s29, 0
	s_mov_b32 m0, s65
	v_lshl_add_u64 v[192:193], s[28:29], 0, v[166:167]
	ds_read_b128 v[146:149], v191 offset:32768
	ds_read_b128 v[150:153], v191 offset:33792
	ds_read_b128 v[154:157], v191 offset:34816
	ds_read_b128 v[158:161], v191 offset:35840
	ds_read_b128 v[162:165], v191 offset:36864
	ds_read_b128 v[176:179], v191 offset:37888
	ds_read_b128 v[180:183], v191 offset:38912
	ds_read_b128 v[184:187], v191 offset:39936
	global_load_lds_dwordx4 v[192:193], off
	v_lshl_add_u64 v[192:193], s[28:29], 0, v[168:169]
	s_mov_b32 m0, s76
	s_nop 0
	global_load_lds_dwordx4 v[192:193], off
	s_waitcnt lgkmcnt(8)
	s_barrier
	s_waitcnt lgkmcnt(0)
	s_setprio 1
	s_waitcnt lgkmcnt(0)
	v_mfma_f32_16x16x32_bf16 v[142:145], v[122:125], v[146:149], v[142:145]
	v_mfma_f32_16x16x32_bf16 v[138:141], v[130:133], v[146:149], v[138:141]
	v_mfma_f32_16x16x32_bf16 v[110:113], v[122:125], v[154:157], v[110:113]
	v_mfma_f32_16x16x32_bf16 v[106:109], v[130:133], v[154:157], v[106:109]
	v_mfma_f32_16x16x32_bf16 v[94:97], v[122:125], v[162:165], v[94:97]
	v_mfma_f32_16x16x32_bf16 v[90:93], v[130:133], v[162:165], v[90:93]
	v_mfma_f32_16x16x32_bf16 v[78:81], v[122:125], v[180:183], v[78:81]
	v_mfma_f32_16x16x32_bf16 v[74:77], v[130:133], v[180:183], v[74:77]
	v_mfma_f32_16x16x32_bf16 v[142:145], v[126:129], v[150:153], v[142:145]
	v_mfma_f32_16x16x32_bf16 v[138:141], v[134:137], v[150:153], v[138:141]
	v_mfma_f32_16x16x32_bf16 v[110:113], v[126:129], v[158:161], v[110:113]
	v_mfma_f32_16x16x32_bf16 v[106:109], v[134:137], v[158:161], v[106:109]
	v_mfma_f32_16x16x32_bf16 v[94:97], v[126:129], v[176:179], v[94:97]
	v_mfma_f32_16x16x32_bf16 v[90:93], v[134:137], v[176:179], v[90:93]
	v_mfma_f32_16x16x32_bf16 v[78:81], v[126:129], v[184:187], v[78:81]
	v_mfma_f32_16x16x32_bf16 v[74:77], v[134:137], v[184:187], v[74:77]
	s_setprio 0
	s_barrier
	s_add_i32 s28, 0, 0x1c000
	s_add_i32 s29, s84, s63
	v_add_u32_e32 v204, s28, v189
	v_lshl_add_u64 v[208:209], v[208:209], 0, s[56:57]
	s_mov_b32 m0, s29
	ds_read_b128 v[192:195], v204
	ds_read_b128 v[196:199], v204 offset:1024
	ds_read_b128 v[200:203], v204 offset:2048
	ds_read_b128 v[204:207], v204 offset:3072
	global_load_lds_dwordx4 v[208:209], off
	v_lshl_add_u64 v[208:209], v[212:213], 0, s[56:57]
	s_add_i32 m0, s29, 0x2000
	s_nop 0
	global_load_lds_dwordx4 v[208:209], off
	s_barrier
	s_waitcnt lgkmcnt(0)
	s_setprio 1
	s_waitcnt lgkmcnt(0)
	v_mfma_f32_16x16x32_bf16 v[118:121], v[192:195], v[146:149], v[118:121]
	v_mfma_f32_16x16x32_bf16 v[114:117], v[200:203], v[146:149], v[114:117]
	v_mfma_f32_16x16x32_bf16 v[102:105], v[192:195], v[154:157], v[102:105]
	v_mfma_f32_16x16x32_bf16 v[98:101], v[200:203], v[154:157], v[98:101]
	v_mfma_f32_16x16x32_bf16 v[86:89], v[192:195], v[162:165], v[86:89]
	v_mfma_f32_16x16x32_bf16 v[82:85], v[200:203], v[162:165], v[82:85]
	v_mfma_f32_16x16x32_bf16 v[70:73], v[192:195], v[180:183], v[70:73]
	v_mfma_f32_16x16x32_bf16 v[66:69], v[200:203], v[180:183], v[66:69]
	v_mfma_f32_16x16x32_bf16 v[118:121], v[196:199], v[150:153], v[118:121]
	v_mfma_f32_16x16x32_bf16 v[114:117], v[204:207], v[150:153], v[114:117]
	v_mfma_f32_16x16x32_bf16 v[102:105], v[196:199], v[158:161], v[102:105]
	v_mfma_f32_16x16x32_bf16 v[98:101], v[204:207], v[158:161], v[98:101]
	v_mfma_f32_16x16x32_bf16 v[86:89], v[196:199], v[176:179], v[86:89]
	v_mfma_f32_16x16x32_bf16 v[82:85], v[204:207], v[176:179], v[82:85]
	v_mfma_f32_16x16x32_bf16 v[70:73], v[196:199], v[184:187], v[70:73]
	v_mfma_f32_16x16x32_bf16 v[66:69], v[204:207], v[184:187], v[66:69]
	s_setprio 0
	s_mov_b32 m0, s79
	v_lshl_add_u64 v[208:209], v[214:215], 0, s[56:57]
	s_barrier
	ds_read_b128 v[146:149], v191 offset:49152
	ds_read_b128 v[150:153], v191 offset:50176
	ds_read_b128 v[154:157], v191 offset:51200
	ds_read_b128 v[158:161], v191 offset:52224
	ds_read_b128 v[162:165], v191 offset:53248
	ds_read_b128 v[176:179], v191 offset:54272
	ds_read_b128 v[180:183], v191 offset:55296
	ds_read_b128 v[184:187], v191 offset:56320
	global_load_lds_dwordx4 v[208:209], off
	v_lshl_add_u64 v[208:209], v[216:217], 0, s[56:57]
	s_mov_b32 m0, s80
	s_nop 0
	global_load_lds_dwordx4 v[208:209], off
	s_barrier
	s_waitcnt lgkmcnt(0)
	s_setprio 1
	s_waitcnt lgkmcnt(0)
	v_mfma_f32_16x16x32_bf16 v[62:65], v[122:125], v[146:149], v[62:65]
	v_mfma_f32_16x16x32_bf16 v[58:61], v[130:133], v[146:149], v[58:61]
	v_mfma_f32_16x16x32_bf16 v[46:49], v[122:125], v[154:157], v[46:49]
	v_mfma_f32_16x16x32_bf16 v[42:45], v[130:133], v[154:157], v[42:45]
	v_mfma_f32_16x16x32_bf16 v[30:33], v[122:125], v[162:165], v[30:33]
	v_mfma_f32_16x16x32_bf16 v[26:29], v[130:133], v[162:165], v[26:29]
	v_mfma_f32_16x16x32_bf16 v[14:17], v[122:125], v[180:183], v[14:17]
	v_mfma_f32_16x16x32_bf16 v[10:13], v[130:133], v[180:183], v[10:13]
	v_mfma_f32_16x16x32_bf16 v[62:65], v[126:129], v[150:153], v[62:65]
	v_mfma_f32_16x16x32_bf16 v[58:61], v[134:137], v[150:153], v[58:61]
	v_mfma_f32_16x16x32_bf16 v[46:49], v[126:129], v[158:161], v[46:49]
	v_mfma_f32_16x16x32_bf16 v[42:45], v[134:137], v[158:161], v[42:45]
	v_mfma_f32_16x16x32_bf16 v[30:33], v[126:129], v[176:179], v[30:33]
	v_mfma_f32_16x16x32_bf16 v[26:29], v[134:137], v[176:179], v[26:29]
	v_mfma_f32_16x16x32_bf16 v[14:17], v[126:129], v[184:187], v[14:17]
	v_mfma_f32_16x16x32_bf16 v[10:13], v[134:137], v[184:187], v[10:13]
	s_setprio 0
	s_barrier
	s_add_u32 s22, s22, 0x40080
	s_addc_u32 s23, s23, 0
	s_add_i32 s28, s28, s63
	v_lshl_add_u64 v[122:123], s[22:23], 0, v[0:1]
	s_mov_b32 m0, s28
	s_nop 0
	global_load_lds_dwordx4 v[122:123], off
	v_lshl_add_u64 v[122:123], s[22:23], 0, v[170:171]
	s_add_i32 m0, s28, 0x2000
	s_nop 0
	global_load_lds_dwordx4 v[122:123], off
	s_waitcnt vmcnt(6)
	s_barrier
	s_setprio 1
	v_mfma_f32_16x16x32_bf16 v[54:57], v[192:195], v[146:149], v[54:57]
	v_mfma_f32_16x16x32_bf16 v[50:53], v[200:203], v[146:149], v[50:53]
	v_mfma_f32_16x16x32_bf16 v[38:41], v[192:195], v[154:157], v[38:41]
	v_mfma_f32_16x16x32_bf16 v[34:37], v[200:203], v[154:157], v[34:37]
	v_mfma_f32_16x16x32_bf16 v[22:25], v[192:195], v[162:165], v[22:25]
	v_mfma_f32_16x16x32_bf16 v[18:21], v[200:203], v[162:165], v[18:21]
	v_mfma_f32_16x16x32_bf16 v[6:9], v[192:195], v[180:183], v[6:9]
	v_mfma_f32_16x16x32_bf16 v[2:5], v[200:203], v[180:183], v[2:5]
	v_mfma_f32_16x16x32_bf16 v[54:57], v[196:199], v[150:153], v[54:57]
	v_mfma_f32_16x16x32_bf16 v[50:53], v[204:207], v[150:153], v[50:53]
	v_mfma_f32_16x16x32_bf16 v[38:41], v[196:199], v[158:161], v[38:41]
	v_mfma_f32_16x16x32_bf16 v[34:37], v[204:207], v[158:161], v[34:37]
	v_mfma_f32_16x16x32_bf16 v[22:25], v[196:199], v[176:179], v[22:25]
	v_mfma_f32_16x16x32_bf16 v[18:21], v[204:207], v[176:179], v[18:21]
	v_mfma_f32_16x16x32_bf16 v[6:9], v[196:199], v[184:187], v[6:9]
	v_mfma_f32_16x16x32_bf16 v[2:5], v[204:207], v[184:187], v[2:5]
	s_setprio 0
	s_add_i32 s83, s83, 2
	s_add_u32 s20, s20, 0x100
	s_addc_u32 s21, s21, 0
	s_add_u32 s35, s35, 0x100
	s_addc_u32 s82, s82, 0
	s_cmp_gt_u32 s83, 13
	s_barrier

.LBB0_1205:
	v_mov_b64_e32 v[2:3], s[6:7]
	s_ashr_i32 s13, s12, 31
	v_cmp_lt_i64_e32 vcc, s[14:15], v[2:3]
	s_lshl_b64 s[14:15], s[12:13], 19
	v_readlane_b32 s16, v254, 59
	v_readlane_b32 s17, v254, 60
	s_add_u32 s14, s16, s14
	s_addc_u32 s15, s17, s15
	s_and_b64 s[16:17], vcc, exec
	s_cselect_b32 s13, s15, s23
	s_cselect_b32 s79, s14, s22
	s_ashr_i32 s11, s10, 31
	s_lshl_b64 s[16:17], s[10:11], 19
	s_add_u32 s16, s61, s16
	s_addc_u32 s17, s62, s17
	s_and_b64 s[28:29], vcc, exec
	s_cselect_b32 s11, s17, s35
	s_cselect_b32 s80, s16, s34
	s_add_u32 s22, s22, 0x40080
	s_addc_u32 s23, s23, 0
	s_add_u32 s81, s34, 0x100
	s_addc_u32 s82, s35, 0
	s_mov_b32 s83, -2
	s_add_u32 s28, s22, 0xfffc0080
	s_addc_u32 s29, s23, -1
	s_add_i32 s84, 0, 0x10000
	v_add_u32_e32 v140, s84, v143
	ds_read_b128 v[146:149], v140
	ds_read_b128 v[150:153], v140 offset:1024
	ds_read_b128 v[154:157], v140 offset:2048
	ds_read_b128 v[158:161], v140 offset:3072
	s_cmp_eq_u32 s83, 12
	s_cselect_b32 s35, s13, s29
	s_cselect_b32 s34, s79, s28
	s_cselect_b32 s29, s11, s82
	s_cselect_b32 s28, s80, s81
	v_lshl_add_u64 v[140:141], s[22:23], 0, v[136:137]
	s_add_i32 m0, s19, 0xc000
	ds_read_b128 v[162:165], v145
	ds_read_b128 v[166:169], v145 offset:1024
	ds_read_b128 v[170:173], v145 offset:2048
	ds_read_b128 v[174:177], v145 offset:3072
	ds_read_b128 v[178:181], v145 offset:4096
	ds_read_b128 v[182:185], v145 offset:5120
	ds_read_b128 v[186:189], v145 offset:6144
	ds_read_b128 v[190:193], v145 offset:7168
	global_load_lds_dwordx4 v[140:141], off
	v_lshl_add_u64 v[140:141], s[22:23], 0, v[138:139]
	s_add_i32 m0, s19, 0xe000
	s_nop 0
	global_load_lds_dwordx4 v[140:141], off
	s_waitcnt lgkmcnt(8)
	s_barrier
	s_waitcnt lgkmcnt(0)
	s_setprio 1
	s_waitcnt lgkmcnt(0)
	v_mfma_f32_16x16x32_bf16 v[126:129], v[146:149], v[162:165], 0
	v_mfma_f32_16x16x32_bf16 v[118:121], v[154:157], v[162:165], 0
	v_mfma_f32_16x16x32_bf16 v[110:113], v[146:149], v[170:173], 0
	v_mfma_f32_16x16x32_bf16 v[102:105], v[154:157], v[170:173], 0
	v_mfma_f32_16x16x32_bf16 v[94:97], v[146:149], v[178:181], 0
	v_mfma_f32_16x16x32_bf16 v[86:89], v[154:157], v[178:181], 0
	v_mfma_f32_16x16x32_bf16 v[78:81], v[146:149], v[186:189], 0
	v_mfma_f32_16x16x32_bf16 v[70:73], v[154:157], v[186:189], 0
	v_mfma_f32_16x16x32_bf16 v[126:129], v[150:153], v[166:169], v[126:129]
	v_mfma_f32_16x16x32_bf16 v[118:121], v[158:161], v[166:169], v[118:121]
	v_mfma_f32_16x16x32_bf16 v[110:113], v[150:153], v[174:177], v[110:113]
	v_mfma_f32_16x16x32_bf16 v[102:105], v[158:161], v[174:177], v[102:105]
	v_mfma_f32_16x16x32_bf16 v[94:97], v[150:153], v[182:185], v[94:97]
	v_mfma_f32_16x16x32_bf16 v[86:89], v[158:161], v[182:185], v[86:89]
	v_mfma_f32_16x16x32_bf16 v[78:81], v[150:153], v[190:193], v[78:81]
	v_mfma_f32_16x16x32_bf16 v[70:73], v[158:161], v[190:193], v[70:73]
	s_setprio 0
	s_barrier
	s_add_i32 s86, 0, 0x14000
	v_add_u32_e32 v140, s86, v143
	s_add_i32 s84, s84, s63
	ds_read_b128 v[194:197], v140
	ds_read_b128 v[198:201], v140 offset:1024
	ds_read_b128 v[202:205], v140 offset:2048
	ds_read_b128 v[206:209], v140 offset:3072
	v_lshl_add_u64 v[140:141], s[28:29], 0, v[0:1]
	s_mov_b32 m0, s84
	v_lshl_add_u64 v[212:213], s[28:29], 0, v[134:135]
	global_load_lds_dwordx4 v[140:141], off
	s_add_i32 m0, s84, 0x2000
	s_nop 0
	global_load_lds_dwordx4 v[212:213], off
	s_barrier
	s_waitcnt lgkmcnt(0)
	s_setprio 1
	s_waitcnt lgkmcnt(0)
	v_mfma_f32_16x16x32_bf16 v[122:125], v[194:197], v[162:165], 0
	v_mfma_f32_16x16x32_bf16 v[114:117], v[202:205], v[162:165], 0
	v_mfma_f32_16x16x32_bf16 v[106:109], v[194:197], v[170:173], 0
	v_mfma_f32_16x16x32_bf16 v[98:101], v[202:205], v[170:173], 0
	v_mfma_f32_16x16x32_bf16 v[90:93], v[194:197], v[178:181], 0
	v_mfma_f32_16x16x32_bf16 v[82:85], v[202:205], v[178:181], 0
	v_mfma_f32_16x16x32_bf16 v[74:77], v[194:197], v[186:189], 0
	v_mfma_f32_16x16x32_bf16 v[66:69], v[202:205], v[186:189], 0
	v_mfma_f32_16x16x32_bf16 v[122:125], v[198:201], v[166:169], v[122:125]
	v_mfma_f32_16x16x32_bf16 v[114:117], v[206:209], v[166:169], v[114:117]
	v_mfma_f32_16x16x32_bf16 v[106:109], v[198:201], v[174:177], v[106:109]
	v_mfma_f32_16x16x32_bf16 v[98:101], v[206:209], v[174:177], v[98:101]
	v_mfma_f32_16x16x32_bf16 v[90:93], v[198:201], v[182:185], v[90:93]
	v_mfma_f32_16x16x32_bf16 v[82:85], v[206:209], v[182:185], v[82:85]
	v_mfma_f32_16x16x32_bf16 v[74:77], v[198:201], v[190:193], v[74:77]
	v_mfma_f32_16x16x32_bf16 v[66:69], v[206:209], v[190:193], v[66:69]
	s_setprio 0
	s_mov_b32 m0, s19
	v_lshl_add_u64 v[214:215], s[34:35], 0, v[130:131]
	s_barrier
	ds_read_b128 v[162:165], v145 offset:16384
	ds_read_b128 v[166:169], v145 offset:17408
	ds_read_b128 v[170:173], v145 offset:18432
	ds_read_b128 v[174:177], v145 offset:19456
	ds_read_b128 v[178:181], v145 offset:20480
	ds_read_b128 v[182:185], v145 offset:21504
	ds_read_b128 v[186:189], v145 offset:22528
	ds_read_b128 v[190:193], v145 offset:23552
	global_load_lds_dwordx4 v[214:215], off
	v_lshl_add_u64 v[216:217], s[34:35], 0, v[132:133]
	s_mov_b32 m0, s21
	s_nop 0
	global_load_lds_dwordx4 v[216:217], off
	s_barrier
	s_waitcnt lgkmcnt(0)
	s_setprio 1
	s_waitcnt lgkmcnt(0)
	v_mfma_f32_16x16x32_bf16 v[62:65], v[146:149], v[162:165], 0
	v_mfma_f32_16x16x32_bf16 v[54:57], v[154:157], v[162:165], 0
	v_mfma_f32_16x16x32_bf16 v[46:49], v[146:149], v[170:173], 0
	v_mfma_f32_16x16x32_bf16 v[38:41], v[154:157], v[170:173], 0
	v_mfma_f32_16x16x32_bf16 v[30:33], v[146:149], v[178:181], 0
	v_mfma_f32_16x16x32_bf16 v[22:25], v[154:157], v[178:181], 0
	v_mfma_f32_16x16x32_bf16 v[14:17], v[146:149], v[186:189], 0
	v_mfma_f32_16x16x32_bf16 v[6:9], v[154:157], v[186:189], 0
	v_mfma_f32_16x16x32_bf16 v[62:65], v[150:153], v[166:169], v[62:65]
	v_mfma_f32_16x16x32_bf16 v[54:57], v[158:161], v[166:169], v[54:57]
	v_mfma_f32_16x16x32_bf16 v[46:49], v[150:153], v[174:177], v[46:49]
	v_mfma_f32_16x16x32_bf16 v[38:41], v[158:161], v[174:177], v[38:41]
	v_mfma_f32_16x16x32_bf16 v[30:33], v[150:153], v[182:185], v[30:33]
	v_mfma_f32_16x16x32_bf16 v[22:25], v[158:161], v[182:185], v[22:25]
	v_mfma_f32_16x16x32_bf16 v[14:17], v[150:153], v[190:193], v[14:17]
	v_mfma_f32_16x16x32_bf16 v[6:9], v[158:161], v[190:193], v[6:9]
	s_setprio 0
	s_barrier
	s_add_u32 s84, s28, 0x40000
	s_addc_u32 s85, s29, 0
	s_add_i32 s86, s86, s63
	v_lshl_add_u64 v[146:147], s[84:85], 0, v[0:1]
	s_mov_b32 m0, s86
	s_nop 0
	global_load_lds_dwordx4 v[146:147], off
	v_lshl_add_u64 v[146:147], s[84:85], 0, v[134:135]
	s_add_i32 m0, s86, 0x2000
	s_nop 0
	global_load_lds_dwordx4 v[146:147], off
	s_waitcnt vmcnt(6)
	s_barrier
	s_setprio 1
	v_mfma_f32_16x16x32_bf16 v[58:61], v[194:197], v[162:165], 0
	v_mfma_f32_16x16x32_bf16 v[50:53], v[202:205], v[162:165], 0
	v_mfma_f32_16x16x32_bf16 v[42:45], v[194:197], v[170:173], 0
	v_mfma_f32_16x16x32_bf16 v[34:37], v[202:205], v[170:173], 0
	v_mfma_f32_16x16x32_bf16 v[26:29], v[194:197], v[178:181], 0
	v_mfma_f32_16x16x32_bf16 v[18:21], v[202:205], v[178:181], 0
	v_mfma_f32_16x16x32_bf16 v[10:13], v[194:197], v[186:189], 0
	v_mfma_f32_16x16x32_bf16 v[2:5], v[202:205], v[186:189], 0
	v_mfma_f32_16x16x32_bf16 v[58:61], v[198:201], v[166:169], v[58:61]
	v_mfma_f32_16x16x32_bf16 v[50:53], v[206:209], v[166:169], v[50:53]
	v_mfma_f32_16x16x32_bf16 v[42:45], v[198:201], v[174:177], v[42:45]
	v_mfma_f32_16x16x32_bf16 v[34:37], v[206:209], v[174:177], v[34:37]
	v_mfma_f32_16x16x32_bf16 v[26:29], v[198:201], v[182:185], v[26:29]
	v_mfma_f32_16x16x32_bf16 v[18:21], v[206:209], v[182:185], v[18:21]
	v_mfma_f32_16x16x32_bf16 v[10:13], v[198:201], v[190:193], v[10:13]
	v_mfma_f32_16x16x32_bf16 v[2:5], v[206:209], v[190:193], v[2:5]
	s_setprio 0
	s_add_i32 s84, 0, 0x18000
	v_add_u32_e32 v158, s84, v143
	s_barrier
	ds_read_b128 v[146:149], v158
	ds_read_b128 v[150:153], v158 offset:1024
	ds_read_b128 v[154:157], v158 offset:2048
	ds_read_b128 v[158:161], v158 offset:3072
	s_add_u32 s34, s34, 0x40000
	s_addc_u32 s35, s35, 0
	s_mov_b32 m0, s64
	v_lshl_add_u64 v[194:195], s[34:35], 0, v[130:131]
	ds_read_b128 v[162:165], v145 offset:32768
	ds_read_b128 v[166:169], v145 offset:33792
	ds_read_b128 v[170:173], v145 offset:34816
	ds_read_b128 v[174:177], v145 offset:35840
	ds_read_b128 v[178:181], v145 offset:36864
	ds_read_b128 v[182:185], v145 offset:37888
	ds_read_b128 v[186:189], v145 offset:38912
	ds_read_b128 v[190:193], v145 offset:39936
	global_load_lds_dwordx4 v[194:195], off
	v_lshl_add_u64 v[194:195], s[34:35], 0, v[132:133]
	s_mov_b32 m0, s65
	s_nop 0
	global_load_lds_dwordx4 v[194:195], off
	s_waitcnt lgkmcnt(8)
	s_barrier
	s_waitcnt lgkmcnt(0)
	s_setprio 1
	s_waitcnt lgkmcnt(0)
	v_mfma_f32_16x16x32_bf16 v[126:129], v[146:149], v[162:165], v[126:129]
	v_mfma_f32_16x16x32_bf16 v[118:121], v[154:157], v[162:165], v[118:121]
	v_mfma_f32_16x16x32_bf16 v[110:113], v[146:149], v[170:173], v[110:113]
	v_mfma_f32_16x16x32_bf16 v[102:105], v[154:157], v[170:173], v[102:105]
	v_mfma_f32_16x16x32_bf16 v[94:97], v[146:149], v[178:181], v[94:97]
	v_mfma_f32_16x16x32_bf16 v[86:89], v[154:157], v[178:181], v[86:89]
	v_mfma_f32_16x16x32_bf16 v[78:81], v[146:149], v[186:189], v[78:81]
	v_mfma_f32_16x16x32_bf16 v[70:73], v[154:157], v[186:189], v[70:73]
	v_mfma_f32_16x16x32_bf16 v[126:129], v[150:153], v[166:169], v[126:129]
	v_mfma_f32_16x16x32_bf16 v[118:121], v[158:161], v[166:169], v[118:121]
	v_mfma_f32_16x16x32_bf16 v[110:113], v[150:153], v[174:177], v[110:113]
	v_mfma_f32_16x16x32_bf16 v[102:105], v[158:161], v[174:177], v[102:105]
	v_mfma_f32_16x16x32_bf16 v[94:97], v[150:153], v[182:185], v[94:97]
	v_mfma_f32_16x16x32_bf16 v[86:89], v[158:161], v[182:185], v[86:89]
	v_mfma_f32_16x16x32_bf16 v[78:81], v[150:153], v[190:193], v[78:81]
	v_mfma_f32_16x16x32_bf16 v[70:73], v[158:161], v[190:193], v[70:73]
	s_setprio 0
	s_barrier
	s_add_i32 s34, 0, 0x1c000
	s_add_i32 s35, s84, s63
	v_add_u32_e32 v206, s34, v143
	v_lshl_add_u64 v[140:141], v[140:141], 0, s[56:57]
	s_mov_b32 m0, s35
	ds_read_b128 v[194:197], v206
	ds_read_b128 v[198:201], v206 offset:1024
	ds_read_b128 v[202:205], v206 offset:2048
	ds_read_b128 v[206:209], v206 offset:3072
	global_load_lds_dwordx4 v[140:141], off
	v_lshl_add_u64 v[140:141], v[212:213], 0, s[56:57]
	s_add_i32 m0, s35, 0x2000
	s_nop 0
	global_load_lds_dwordx4 v[140:141], off
	s_barrier
	s_waitcnt lgkmcnt(0)
	s_setprio 1
	s_waitcnt lgkmcnt(0)
	v_mfma_f32_16x16x32_bf16 v[122:125], v[194:197], v[162:165], v[122:125]
	v_mfma_f32_16x16x32_bf16 v[114:117], v[202:205], v[162:165], v[114:117]
	v_mfma_f32_16x16x32_bf16 v[106:109], v[194:197], v[170:173], v[106:109]
	v_mfma_f32_16x16x32_bf16 v[98:101], v[202:205], v[170:173], v[98:101]
	v_mfma_f32_16x16x32_bf16 v[90:93], v[194:197], v[178:181], v[90:93]
	v_mfma_f32_16x16x32_bf16 v[82:85], v[202:205], v[178:181], v[82:85]
	v_mfma_f32_16x16x32_bf16 v[74:77], v[194:197], v[186:189], v[74:77]
	v_mfma_f32_16x16x32_bf16 v[66:69], v[202:205], v[186:189], v[66:69]
	v_mfma_f32_16x16x32_bf16 v[122:125], v[198:201], v[166:169], v[122:125]
	v_mfma_f32_16x16x32_bf16 v[114:117], v[206:209], v[166:169], v[114:117]
	v_mfma_f32_16x16x32_bf16 v[106:109], v[198:201], v[174:177], v[106:109]
	v_mfma_f32_16x16x32_bf16 v[98:101], v[206:209], v[174:177], v[98:101]
	v_mfma_f32_16x16x32_bf16 v[90:93], v[198:201], v[182:185], v[90:93]
	v_mfma_f32_16x16x32_bf16 v[82:85], v[206:209], v[182:185], v[82:85]
	v_mfma_f32_16x16x32_bf16 v[74:77], v[198:201], v[190:193], v[74:77]
	v_mfma_f32_16x16x32_bf16 v[66:69], v[206:209], v[190:193], v[66:69]
	s_setprio 0
	s_mov_b32 m0, s76
	v_lshl_add_u64 v[140:141], v[214:215], 0, s[56:57]
	s_barrier
	ds_read_b128 v[162:165], v145 offset:49152
	ds_read_b128 v[166:169], v145 offset:50176
	ds_read_b128 v[170:173], v145 offset:51200
	ds_read_b128 v[174:177], v145 offset:52224
	ds_read_b128 v[178:181], v145 offset:53248
	ds_read_b128 v[182:185], v145 offset:54272
	ds_read_b128 v[186:189], v145 offset:55296
	ds_read_b128 v[190:193], v145 offset:56320
	global_load_lds_dwordx4 v[140:141], off
	v_lshl_add_u64 v[140:141], v[216:217], 0, s[56:57]
	s_mov_b32 m0, s77
	s_nop 0
	global_load_lds_dwordx4 v[140:141], off
	s_barrier
	s_waitcnt lgkmcnt(0)
	s_setprio 1
	s_waitcnt lgkmcnt(0)
	v_mfma_f32_16x16x32_bf16 v[62:65], v[146:149], v[162:165], v[62:65]
	v_mfma_f32_16x16x32_bf16 v[54:57], v[154:157], v[162:165], v[54:57]
	v_mfma_f32_16x16x32_bf16 v[46:49], v[146:149], v[170:173], v[46:49]
	v_mfma_f32_16x16x32_bf16 v[38:41], v[154:157], v[170:173], v[38:41]
	v_mfma_f32_16x16x32_bf16 v[30:33], v[146:149], v[178:181], v[30:33]
	v_mfma_f32_16x16x32_bf16 v[22:25], v[154:157], v[178:181], v[22:25]
	v_mfma_f32_16x16x32_bf16 v[14:17], v[146:149], v[186:189], v[14:17]
	v_mfma_f32_16x16x32_bf16 v[6:9], v[154:157], v[186:189], v[6:9]
	v_mfma_f32_16x16x32_bf16 v[62:65], v[150:153], v[166:169], v[62:65]
	v_mfma_f32_16x16x32_bf16 v[54:57], v[158:161], v[166:169], v[54:57]
	v_mfma_f32_16x16x32_bf16 v[46:49], v[150:153], v[174:177], v[46:49]
	v_mfma_f32_16x16x32_bf16 v[38:41], v[158:161], v[174:177], v[38:41]
	v_mfma_f32_16x16x32_bf16 v[30:33], v[150:153], v[182:185], v[30:33]
	v_mfma_f32_16x16x32_bf16 v[22:25], v[158:161], v[182:185], v[22:25]
	v_mfma_f32_16x16x32_bf16 v[14:17], v[150:153], v[190:193], v[14:17]
	v_mfma_f32_16x16x32_bf16 v[6:9], v[158:161], v[190:193], v[6:9]
	s_setprio 0
	s_barrier
	s_add_u32 s28, s28, 0x40080
	s_addc_u32 s29, s29, 0
	s_add_i32 s34, s34, s63
	v_lshl_add_u64 v[140:141], s[28:29], 0, v[0:1]
	s_mov_b32 m0, s34
	s_nop 0
	global_load_lds_dwordx4 v[140:141], off
	v_lshl_add_u64 v[140:141], s[28:29], 0, v[134:135]
	s_add_i32 m0, s34, 0x2000
	s_nop 0
	global_load_lds_dwordx4 v[140:141], off
	s_waitcnt vmcnt(6)
	s_barrier
	s_setprio 1
	v_mfma_f32_16x16x32_bf16 v[58:61], v[194:197], v[162:165], v[58:61]
	v_mfma_f32_16x16x32_bf16 v[50:53], v[202:205], v[162:165], v[50:53]
	v_mfma_f32_16x16x32_bf16 v[42:45], v[194:197], v[170:173], v[42:45]
	v_mfma_f32_16x16x32_bf16 v[34:37], v[202:205], v[170:173], v[34:37]
	v_mfma_f32_16x16x32_bf16 v[26:29], v[194:197], v[178:181], v[26:29]
	v_mfma_f32_16x16x32_bf16 v[18:21], v[202:205], v[178:181], v[18:21]
	v_mfma_f32_16x16x32_bf16 v[10:13], v[194:197], v[186:189], v[10:13]
	v_mfma_f32_16x16x32_bf16 v[2:5], v[202:205], v[186:189], v[2:5]
	v_mfma_f32_16x16x32_bf16 v[58:61], v[198:201], v[166:169], v[58:61]
	v_mfma_f32_16x16x32_bf16 v[50:53], v[206:209], v[166:169], v[50:53]
	v_mfma_f32_16x16x32_bf16 v[42:45], v[198:201], v[174:177], v[42:45]
	v_mfma_f32_16x16x32_bf16 v[34:37], v[206:209], v[174:177], v[34:37]
	v_mfma_f32_16x16x32_bf16 v[26:29], v[198:201], v[182:185], v[26:29]
	v_mfma_f32_16x16x32_bf16 v[18:21], v[206:209], v[182:185], v[18:21]
	v_mfma_f32_16x16x32_bf16 v[10:13], v[198:201], v[190:193], v[10:13]
	v_mfma_f32_16x16x32_bf16 v[2:5], v[206:209], v[190:193], v[2:5]
	s_setprio 0
	s_add_i32 s83, s83, 2
	s_add_u32 s22, s22, 0x100
	s_addc_u32 s23, s23, 0
	s_add_u32 s81, s81, 0x100
	s_addc_u32 s82, s82, 0
	s_cmp_gt_u32 s83, 13
	s_barrier

.LBB0_1277:
	s_add_u32 s13, s16, 0x100
	s_addc_u32 s75, s17, 0
	s_mov_b32 s77, -2
	s_add_u32 s10, s14, 0x100
	s_addc_u32 s11, s15, 0
	s_add_i32 s78, 0, 0x10000
	v_add_u32_e32 v134, s78, v191
	ds_read_b128 v[122:125], v134
	ds_read_b128 v[126:129], v134 offset:1024
	ds_read_b128 v[130:133], v134 offset:2048
	ds_read_b128 v[134:137], v134 offset:3072
	s_cmp_eq_u32 s77, 40
	s_cselect_b32 s19, s7, s11
	s_cselect_b32 s18, s6, s10
	s_cselect_b32 s17, s9, s75
	s_cselect_b32 s16, s8, s13
	v_lshl_add_u64 v[188:189], s[14:15], 0, v[172:173]
	s_add_i32 m0, s25, 0xc000
	ds_read_b128 v[146:149], v193
	ds_read_b128 v[150:153], v193 offset:1024
	ds_read_b128 v[154:157], v193 offset:2048
	ds_read_b128 v[158:161], v193 offset:3072
	ds_read_b128 v[162:165], v193 offset:4096
	ds_read_b128 v[176:179], v193 offset:5120
	ds_read_b128 v[180:183], v193 offset:6144
	ds_read_b128 v[184:187], v193 offset:7168
	global_load_lds_dwordx4 v[188:189], off
	v_lshl_add_u64 v[188:189], s[14:15], 0, v[174:175]
	s_add_i32 m0, s25, 0xe000
	s_nop 0
	global_load_lds_dwordx4 v[188:189], off
	s_waitcnt lgkmcnt(8)
	s_barrier
	s_waitcnt lgkmcnt(0)
	s_setprio 1
	s_waitcnt lgkmcnt(0)
	v_mfma_f32_16x16x32_bf16 v[142:145], v[122:125], v[146:149], 0
	v_mfma_f32_16x16x32_bf16 v[138:141], v[130:133], v[146:149], 0
	v_mfma_f32_16x16x32_bf16 v[110:113], v[122:125], v[154:157], 0
	v_mfma_f32_16x16x32_bf16 v[106:109], v[130:133], v[154:157], 0
	v_mfma_f32_16x16x32_bf16 v[94:97], v[122:125], v[162:165], 0
	v_mfma_f32_16x16x32_bf16 v[90:93], v[130:133], v[162:165], 0
	v_mfma_f32_16x16x32_bf16 v[78:81], v[122:125], v[180:183], 0
	v_mfma_f32_16x16x32_bf16 v[74:77], v[130:133], v[180:183], 0
	v_mfma_f32_16x16x32_bf16 v[142:145], v[126:129], v[150:153], v[142:145]
	v_mfma_f32_16x16x32_bf16 v[138:141], v[134:137], v[150:153], v[138:141]
	v_mfma_f32_16x16x32_bf16 v[110:113], v[126:129], v[158:161], v[110:113]
	v_mfma_f32_16x16x32_bf16 v[106:109], v[134:137], v[158:161], v[106:109]
	v_mfma_f32_16x16x32_bf16 v[94:97], v[126:129], v[176:179], v[94:97]
	v_mfma_f32_16x16x32_bf16 v[90:93], v[134:137], v[176:179], v[90:93]
	v_mfma_f32_16x16x32_bf16 v[78:81], v[126:129], v[184:187], v[78:81]
	v_mfma_f32_16x16x32_bf16 v[74:77], v[134:137], v[184:187], v[74:77]
	s_setprio 0
	s_barrier
	s_add_i32 s79, 0, 0x14000
	v_add_u32_e32 v188, s79, v191
	s_add_i32 s14, s78, s24
	ds_read_b128 v[194:197], v188
	ds_read_b128 v[198:201], v188 offset:1024
	ds_read_b128 v[202:205], v188 offset:2048
	ds_read_b128 v[206:209], v188 offset:3072
	v_lshl_add_u64 v[188:189], s[16:17], 0, v[0:1]
	s_mov_b32 m0, s14
	v_lshl_add_u64 v[212:213], s[16:17], 0, v[170:171]
	global_load_lds_dwordx4 v[188:189], off
	s_add_i32 m0, s14, 0x2000
	s_nop 0
	global_load_lds_dwordx4 v[212:213], off
	s_barrier
	s_waitcnt lgkmcnt(0)
	s_setprio 1
	s_waitcnt lgkmcnt(0)
	v_mfma_f32_16x16x32_bf16 v[118:121], v[194:197], v[146:149], 0
	v_mfma_f32_16x16x32_bf16 v[114:117], v[202:205], v[146:149], 0
	v_mfma_f32_16x16x32_bf16 v[102:105], v[194:197], v[154:157], 0
	v_mfma_f32_16x16x32_bf16 v[98:101], v[202:205], v[154:157], 0
	v_mfma_f32_16x16x32_bf16 v[86:89], v[194:197], v[162:165], 0
	v_mfma_f32_16x16x32_bf16 v[82:85], v[202:205], v[162:165], 0
	v_mfma_f32_16x16x32_bf16 v[70:73], v[194:197], v[180:183], 0
	v_mfma_f32_16x16x32_bf16 v[66:69], v[202:205], v[180:183], 0
	v_mfma_f32_16x16x32_bf16 v[118:121], v[198:201], v[150:153], v[118:121]
	v_mfma_f32_16x16x32_bf16 v[114:117], v[206:209], v[150:153], v[114:117]
	v_mfma_f32_16x16x32_bf16 v[102:105], v[198:201], v[158:161], v[102:105]
	v_mfma_f32_16x16x32_bf16 v[98:101], v[206:209], v[158:161], v[98:101]
	v_mfma_f32_16x16x32_bf16 v[86:89], v[198:201], v[176:179], v[86:89]
	v_mfma_f32_16x16x32_bf16 v[82:85], v[206:209], v[176:179], v[82:85]
	v_mfma_f32_16x16x32_bf16 v[70:73], v[198:201], v[184:187], v[70:73]
	v_mfma_f32_16x16x32_bf16 v[66:69], v[206:209], v[184:187], v[66:69]
	s_setprio 0
	s_mov_b32 m0, s25
	v_lshl_add_u64 v[214:215], s[18:19], 0, v[166:167]
	s_barrier
	ds_read_b128 v[146:149], v193 offset:16384
	ds_read_b128 v[150:153], v193 offset:17408
	ds_read_b128 v[154:157], v193 offset:18432
	ds_read_b128 v[158:161], v193 offset:19456
	ds_read_b128 v[162:165], v193 offset:20480
	ds_read_b128 v[176:179], v193 offset:21504
	ds_read_b128 v[180:183], v193 offset:22528
	ds_read_b128 v[184:187], v193 offset:23552
	global_load_lds_dwordx4 v[214:215], off
	v_lshl_add_u64 v[216:217], s[18:19], 0, v[168:169]
	s_mov_b32 m0, s28
	s_nop 0
	global_load_lds_dwordx4 v[216:217], off
	s_barrier
	s_waitcnt lgkmcnt(0)
	s_setprio 1
	s_waitcnt lgkmcnt(0)
	v_mfma_f32_16x16x32_bf16 v[62:65], v[122:125], v[146:149], 0
	v_mfma_f32_16x16x32_bf16 v[58:61], v[130:133], v[146:149], 0
	v_mfma_f32_16x16x32_bf16 v[46:49], v[122:125], v[154:157], 0
	v_mfma_f32_16x16x32_bf16 v[42:45], v[130:133], v[154:157], 0
	v_mfma_f32_16x16x32_bf16 v[30:33], v[122:125], v[162:165], 0
	v_mfma_f32_16x16x32_bf16 v[26:29], v[130:133], v[162:165], 0
	v_mfma_f32_16x16x32_bf16 v[14:17], v[122:125], v[180:183], 0
	v_mfma_f32_16x16x32_bf16 v[10:13], v[130:133], v[180:183], 0
	v_mfma_f32_16x16x32_bf16 v[62:65], v[126:129], v[150:153], v[62:65]
	v_mfma_f32_16x16x32_bf16 v[58:61], v[134:137], v[150:153], v[58:61]
	v_mfma_f32_16x16x32_bf16 v[46:49], v[126:129], v[158:161], v[46:49]
	v_mfma_f32_16x16x32_bf16 v[42:45], v[134:137], v[158:161], v[42:45]
	v_mfma_f32_16x16x32_bf16 v[30:33], v[126:129], v[176:179], v[30:33]
	v_mfma_f32_16x16x32_bf16 v[26:29], v[134:137], v[176:179], v[26:29]
	v_mfma_f32_16x16x32_bf16 v[14:17], v[126:129], v[184:187], v[14:17]
	v_mfma_f32_16x16x32_bf16 v[10:13], v[134:137], v[184:187], v[10:13]
	s_setprio 0
	s_barrier
	s_add_u32 s14, s16, 0xb0000
	s_addc_u32 s15, s17, 0
	s_add_i32 s78, s79, s24
	v_lshl_add_u64 v[122:123], s[14:15], 0, v[0:1]
	s_mov_b32 m0, s78
	s_nop 0
	global_load_lds_dwordx4 v[122:123], off
	v_lshl_add_u64 v[122:123], s[14:15], 0, v[170:171]
	s_add_i32 m0, s78, 0x2000
	s_nop 0
	global_load_lds_dwordx4 v[122:123], off
	s_waitcnt vmcnt(6)
	s_barrier
	s_setprio 1
	v_mfma_f32_16x16x32_bf16 v[54:57], v[194:197], v[146:149], 0
	v_mfma_f32_16x16x32_bf16 v[50:53], v[202:205], v[146:149], 0
	v_mfma_f32_16x16x32_bf16 v[38:41], v[194:197], v[154:157], 0
	v_mfma_f32_16x16x32_bf16 v[34:37], v[202:205], v[154:157], 0
	v_mfma_f32_16x16x32_bf16 v[22:25], v[194:197], v[162:165], 0
	v_mfma_f32_16x16x32_bf16 v[18:21], v[202:205], v[162:165], 0
	v_mfma_f32_16x16x32_bf16 v[6:9], v[194:197], v[180:183], 0
	v_mfma_f32_16x16x32_bf16 v[2:5], v[202:205], v[180:183], 0
	v_mfma_f32_16x16x32_bf16 v[54:57], v[198:201], v[150:153], v[54:57]
	v_mfma_f32_16x16x32_bf16 v[50:53], v[206:209], v[150:153], v[50:53]
	v_mfma_f32_16x16x32_bf16 v[38:41], v[198:201], v[158:161], v[38:41]
	v_mfma_f32_16x16x32_bf16 v[34:37], v[206:209], v[158:161], v[34:37]
	v_mfma_f32_16x16x32_bf16 v[22:25], v[198:201], v[176:179], v[22:25]
	v_mfma_f32_16x16x32_bf16 v[18:21], v[206:209], v[176:179], v[18:21]
	v_mfma_f32_16x16x32_bf16 v[6:9], v[198:201], v[184:187], v[6:9]
	v_mfma_f32_16x16x32_bf16 v[2:5], v[206:209], v[184:187], v[2:5]
	s_setprio 0
	s_add_i32 s78, 0, 0x18000
	v_add_u32_e32 v134, s78, v191
	s_barrier
	ds_read_b128 v[122:125], v134
	ds_read_b128 v[126:129], v134 offset:1024
	ds_read_b128 v[130:133], v134 offset:2048
	ds_read_b128 v[134:137], v134 offset:3072
	s_add_u32 s14, s18, 0xb0000
	s_addc_u32 s15, s19, 0
	s_mov_b32 m0, s29
	v_lshl_add_u64 v[194:195], s[14:15], 0, v[166:167]
	ds_read_b128 v[146:149], v193 offset:32768
	ds_read_b128 v[150:153], v193 offset:33792
	ds_read_b128 v[154:157], v193 offset:34816
	ds_read_b128 v[158:161], v193 offset:35840
	ds_read_b128 v[162:165], v193 offset:36864
	ds_read_b128 v[176:179], v193 offset:37888
	ds_read_b128 v[180:183], v193 offset:38912
	ds_read_b128 v[184:187], v193 offset:39936
	global_load_lds_dwordx4 v[194:195], off
	v_lshl_add_u64 v[194:195], s[14:15], 0, v[168:169]
	s_mov_b32 m0, s34
	s_nop 0
	global_load_lds_dwordx4 v[194:195], off
	s_waitcnt lgkmcnt(8)
	s_barrier
	s_waitcnt lgkmcnt(0)
	s_setprio 1
	s_waitcnt lgkmcnt(0)
	v_mfma_f32_16x16x32_bf16 v[142:145], v[122:125], v[146:149], v[142:145]
	v_mfma_f32_16x16x32_bf16 v[138:141], v[130:133], v[146:149], v[138:141]
	v_mfma_f32_16x16x32_bf16 v[110:113], v[122:125], v[154:157], v[110:113]
	v_mfma_f32_16x16x32_bf16 v[106:109], v[130:133], v[154:157], v[106:109]
	v_mfma_f32_16x16x32_bf16 v[94:97], v[122:125], v[162:165], v[94:97]
	v_mfma_f32_16x16x32_bf16 v[90:93], v[130:133], v[162:165], v[90:93]
	v_mfma_f32_16x16x32_bf16 v[78:81], v[122:125], v[180:183], v[78:81]
	v_mfma_f32_16x16x32_bf16 v[74:77], v[130:133], v[180:183], v[74:77]
	v_mfma_f32_16x16x32_bf16 v[142:145], v[126:129], v[150:153], v[142:145]
	v_mfma_f32_16x16x32_bf16 v[138:141], v[134:137], v[150:153], v[138:141]
	v_mfma_f32_16x16x32_bf16 v[110:113], v[126:129], v[158:161], v[110:113]
	v_mfma_f32_16x16x32_bf16 v[106:109], v[134:137], v[158:161], v[106:109]
	v_mfma_f32_16x16x32_bf16 v[94:97], v[126:129], v[176:179], v[94:97]
	v_mfma_f32_16x16x32_bf16 v[90:93], v[134:137], v[176:179], v[90:93]
	v_mfma_f32_16x16x32_bf16 v[78:81], v[126:129], v[184:187], v[78:81]
	v_mfma_f32_16x16x32_bf16 v[74:77], v[134:137], v[184:187], v[74:77]
	s_setprio 0
	s_barrier
	s_add_i32 s18, 0, 0x1c000
	s_add_i32 s14, s78, s24
	v_add_u32_e32 v206, s18, v191
	v_lshl_add_u64 v[188:189], v[188:189], 0, s[56:57]
	s_mov_b32 m0, s14
	ds_read_b128 v[194:197], v206
	ds_read_b128 v[198:201], v206 offset:1024
	ds_read_b128 v[202:205], v206 offset:2048
	ds_read_b128 v[206:209], v206 offset:3072
	global_load_lds_dwordx4 v[188:189], off
	v_lshl_add_u64 v[188:189], v[212:213], 0, s[56:57]
	s_add_i32 m0, s14, 0x2000
	s_nop 0
	global_load_lds_dwordx4 v[188:189], off
	s_barrier
	s_waitcnt lgkmcnt(0)
	s_setprio 1
	s_waitcnt lgkmcnt(0)
	v_mfma_f32_16x16x32_bf16 v[118:121], v[194:197], v[146:149], v[118:121]
	v_mfma_f32_16x16x32_bf16 v[114:117], v[202:205], v[146:149], v[114:117]
	v_mfma_f32_16x16x32_bf16 v[102:105], v[194:197], v[154:157], v[102:105]
	v_mfma_f32_16x16x32_bf16 v[98:101], v[202:205], v[154:157], v[98:101]
	v_mfma_f32_16x16x32_bf16 v[86:89], v[194:197], v[162:165], v[86:89]
	v_mfma_f32_16x16x32_bf16 v[82:85], v[202:205], v[162:165], v[82:85]
	v_mfma_f32_16x16x32_bf16 v[70:73], v[194:197], v[180:183], v[70:73]
	v_mfma_f32_16x16x32_bf16 v[66:69], v[202:205], v[180:183], v[66:69]
	v_mfma_f32_16x16x32_bf16 v[118:121], v[198:201], v[150:153], v[118:121]
	v_mfma_f32_16x16x32_bf16 v[114:117], v[206:209], v[150:153], v[114:117]
	v_mfma_f32_16x16x32_bf16 v[102:105], v[198:201], v[158:161], v[102:105]
	v_mfma_f32_16x16x32_bf16 v[98:101], v[206:209], v[158:161], v[98:101]
	v_mfma_f32_16x16x32_bf16 v[86:89], v[198:201], v[176:179], v[86:89]
	v_mfma_f32_16x16x32_bf16 v[82:85], v[206:209], v[176:179], v[82:85]
	v_mfma_f32_16x16x32_bf16 v[70:73], v[198:201], v[184:187], v[70:73]
	v_mfma_f32_16x16x32_bf16 v[66:69], v[206:209], v[184:187], v[66:69]
	s_setprio 0
	s_mov_b32 m0, s62
	v_lshl_add_u64 v[188:189], v[214:215], 0, s[56:57]
	s_barrier
	ds_read_b128 v[146:149], v193 offset:49152
	ds_read_b128 v[150:153], v193 offset:50176
	ds_read_b128 v[154:157], v193 offset:51200
	ds_read_b128 v[158:161], v193 offset:52224
	ds_read_b128 v[162:165], v193 offset:53248
	ds_read_b128 v[176:179], v193 offset:54272
	ds_read_b128 v[180:183], v193 offset:55296
	ds_read_b128 v[184:187], v193 offset:56320
	global_load_lds_dwordx4 v[188:189], off
	v_lshl_add_u64 v[188:189], v[216:217], 0, s[56:57]
	s_mov_b32 m0, s63
	s_nop 0
	global_load_lds_dwordx4 v[188:189], off
	s_barrier
	s_waitcnt lgkmcnt(0)
	s_setprio 1
	s_waitcnt lgkmcnt(0)
	v_mfma_f32_16x16x32_bf16 v[62:65], v[122:125], v[146:149], v[62:65]
	v_mfma_f32_16x16x32_bf16 v[58:61], v[130:133], v[146:149], v[58:61]
	v_mfma_f32_16x16x32_bf16 v[46:49], v[122:125], v[154:157], v[46:49]
	v_mfma_f32_16x16x32_bf16 v[42:45], v[130:133], v[154:157], v[42:45]
	v_mfma_f32_16x16x32_bf16 v[30:33], v[122:125], v[162:165], v[30:33]
	v_mfma_f32_16x16x32_bf16 v[26:29], v[130:133], v[162:165], v[26:29]
	v_mfma_f32_16x16x32_bf16 v[14:17], v[122:125], v[180:183], v[14:17]
	v_mfma_f32_16x16x32_bf16 v[10:13], v[130:133], v[180:183], v[10:13]
	v_mfma_f32_16x16x32_bf16 v[62:65], v[126:129], v[150:153], v[62:65]
	v_mfma_f32_16x16x32_bf16 v[58:61], v[134:137], v[150:153], v[58:61]
	v_mfma_f32_16x16x32_bf16 v[46:49], v[126:129], v[158:161], v[46:49]
	v_mfma_f32_16x16x32_bf16 v[42:45], v[134:137], v[158:161], v[42:45]
	v_mfma_f32_16x16x32_bf16 v[30:33], v[126:129], v[176:179], v[30:33]
	v_mfma_f32_16x16x32_bf16 v[26:29], v[134:137], v[176:179], v[26:29]
	v_mfma_f32_16x16x32_bf16 v[14:17], v[126:129], v[184:187], v[14:17]
	v_mfma_f32_16x16x32_bf16 v[10:13], v[134:137], v[184:187], v[10:13]
	s_setprio 0
	s_barrier
	s_add_u32 s14, s16, 0xb0080
	s_addc_u32 s15, s17, 0
	s_add_i32 s16, s18, s24
	v_lshl_add_u64 v[122:123], s[14:15], 0, v[0:1]
	s_mov_b32 m0, s16
	s_nop 0
	global_load_lds_dwordx4 v[122:123], off
	v_lshl_add_u64 v[122:123], s[14:15], 0, v[170:171]
	s_add_i32 m0, s16, 0x2000
	s_nop 0
	global_load_lds_dwordx4 v[122:123], off
	s_waitcnt vmcnt(6)
	s_barrier
	s_setprio 1
	v_mfma_f32_16x16x32_bf16 v[54:57], v[194:197], v[146:149], v[54:57]
	v_mfma_f32_16x16x32_bf16 v[50:53], v[202:205], v[146:149], v[50:53]
	v_mfma_f32_16x16x32_bf16 v[38:41], v[194:197], v[154:157], v[38:41]
	v_mfma_f32_16x16x32_bf16 v[34:37], v[202:205], v[154:157], v[34:37]
	v_mfma_f32_16x16x32_bf16 v[22:25], v[194:197], v[162:165], v[22:25]
	v_mfma_f32_16x16x32_bf16 v[18:21], v[202:205], v[162:165], v[18:21]
	v_mfma_f32_16x16x32_bf16 v[6:9], v[194:197], v[180:183], v[6:9]
	v_mfma_f32_16x16x32_bf16 v[2:5], v[202:205], v[180:183], v[2:5]
	v_mfma_f32_16x16x32_bf16 v[54:57], v[198:201], v[150:153], v[54:57]
	v_mfma_f32_16x16x32_bf16 v[50:53], v[206:209], v[150:153], v[50:53]
	v_mfma_f32_16x16x32_bf16 v[38:41], v[198:201], v[158:161], v[38:41]
	v_mfma_f32_16x16x32_bf16 v[34:37], v[206:209], v[158:161], v[34:37]
	v_mfma_f32_16x16x32_bf16 v[22:25], v[198:201], v[176:179], v[22:25]
	v_mfma_f32_16x16x32_bf16 v[18:21], v[206:209], v[176:179], v[18:21]
	v_mfma_f32_16x16x32_bf16 v[6:9], v[198:201], v[184:187], v[6:9]
	v_mfma_f32_16x16x32_bf16 v[2:5], v[206:209], v[184:187], v[2:5]
	s_setprio 0
	s_add_i32 s77, s77, 2
	s_add_u32 s13, s13, 0x100
	s_addc_u32 s75, s75, 0
	s_cmp_gt_u32 s77, 41
	s_mov_b64 s[14:15], s[10:11]
	s_barrier
